# K-loop: dedupe lgkmcnt(0), post-MFMA SALU moved into MFMA shadow, drop m0 s_nop; FF1 epilogue: drop canonicalizing v_max
# speedup vs baseline: 1.0215x; 1.0215x over previous
; #define PG8_STAGE(bufoff, gbase, voff) do { _Pragma("unroll") for (int _i = 0; _i < 2; ++_i) \
;         __builtin_amdgcn_global_load_lds((const unsigned*)((const char*)(gbase) + (voff)[_i]), (LAS unsigned*)(lds + (bufoff) + ldsw + _i * 8192), 16, 0, 0); } while (0)
; #define PG8_LDA(dst, b, h) do { _Pragma("unroll") for (int m = 0; m < 4; ++m) _Pragma("unroll") for (int k = 0; k < 2; ++k) dst[m][k] = *(const LAS bf16x8*)(lds + PG8_SA(b, h) + aoff + m * 2048 + k * 1024); } while (0)
; #define PG8_LDB(dst, b, h) do { _Pragma("unroll") for (int n = 0; n < 2; ++n) _Pragma("unroll") for (int k = 0; k < 2; ++k) dst[n][k] = *(const LAS bf16x8*)(lds + PG8_SB(b, h) + boff + n * 2048 + k * 1024); } while (0)
; #define PG8_MMA(ai, bj, At, Bt) do { __builtin_amdgcn_s_setprio(1); _Pragma("unroll") for (int m = 0; m < 4; ++m) _Pragma("unroll") for (int n = 0; n < 2; ++n) _Pragma("unroll") for (int k = 0; k < 2; ++k) \
;         acc[ai][bj][m][n] = __builtin_amdgcn_mfma_f32_16x16x32_bf16(Bt[n][k], At[m][k], acc[ai][bj][m][n], 0, 0, 0); __builtin_amdgcn_s_setprio(0); } while (0)
; #define PG8_WAIT_L(n) asm volatile("s_waitcnt lgkmcnt(" #n ")" ::: "memory")
; #define PG8_BAR __builtin_amdgcn_s_barrier()
; #define PG8_SCHED __builtin_amdgcn_sched_barrier(0)
; template <class Epi>
; __device__ __forceinline__ void gemm_phase(LAS unsigned char* lds, const Gemm g, const StaticOrder& S, const Epi& E) {
;     ...
;             const bool last = (t == nt - 2);
;             const char* a1 = cA + (size_t)(t + 1) * kstep;
;             const char* a2 = last ? nA : cA + (size_t)(t + 2) * kstep; const char* b2 = last ? nB : cB + (size_t)(t + 2) * kstep;
;             const char* a3 = a2 + kstep; const char* b3 = b2 + kstep;
;             PG8_LDB(B0, 0, 0); PG8_SCHED; PG8_LDA(At, 0, 0); PG8_STAGE(PG8_SA(1, 1), a1 + hstepA, voffA);
;             PG8_WAIT_L(8); PG8_BAR; PG8_WAIT_L(0); PG8_MMA(0, 0, At, B0); PG8_BAR; PG8_SCHED;
;             PG8_LDB(B1, 0, 1); PG8_STAGE(PG8_SB(0, 0), b2, voffB);
;             PG8_BAR; PG8_WAIT_L(0); PG8_MMA(0, 1, At, B1); PG8_BAR;
;             PG8_LDA(At, 0, 1); PG8_STAGE(PG8_SA(0, 0), a2, voffA);
;             PG8_BAR; PG8_WAIT_L(0); PG8_MMA(1, 0, At, B0); PG8_BAR; PG8_SCHED;
.LBB0_141:
	s_add_u32 s24, s22, 0xfff84000
	s_addc_u32 s25, s23, -1
	s_cmp_eq_u32 s54, 28
	s_cselect_b32 s28, s49, s24
	s_cselect_b32 s29, s15, s25
	s_cselect_b32 s24, s50, s51
	s_cselect_b32 s25, s5, s52
	s_add_u32 s26, s28, 0x4000
	s_addc_u32 s27, s29, 0
	s_add_i32 s55, 0, 0x10000
	v_add_u32_e32 v148, s55, v134
	ds_read_b128 v[136:139], v148
	ds_read_b128 v[140:143], v148 offset:1024
	ds_read_b128 v[144:147], v148 offset:2048
	ds_read_b128 v[148:151], v148 offset:3072
	v_lshl_add_u64 v[188:189], s[22:23], 0, v[128:129]
	s_add_i32 m0, s37, 0xc000
	ds_read_b128 v[156:159], v135
	ds_read_b128 v[160:163], v135 offset:1024
	ds_read_b128 v[164:167], v135 offset:2048
	ds_read_b128 v[168:171], v135 offset:3072
	ds_read_b128 v[172:175], v135 offset:4096
	ds_read_b128 v[176:179], v135 offset:5120
	ds_read_b128 v[180:183], v135 offset:6144
	ds_read_b128 v[184:187], v135 offset:7168
	global_load_lds_dwordx4 v[188:189], off
	s_add_i32 m0, s37, 0xe000
	v_lshl_add_u64 v[188:189], s[22:23], 0, v[130:131]
	global_load_lds_dwordx4 v[188:189], off
	s_waitcnt lgkmcnt(8)
	s_barrier
	s_waitcnt lgkmcnt(0)
	s_setprio 1
	v_mfma_f32_16x16x32_bf16 v[124:127], v[136:139], v[156:159], v[124:127]
	v_mfma_f32_16x16x32_bf16 v[120:123], v[144:147], v[156:159], v[120:123]
	v_mfma_f32_16x16x32_bf16 v[108:111], v[136:139], v[164:167], v[108:111]
	v_mfma_f32_16x16x32_bf16 v[104:107], v[144:147], v[164:167], v[104:107]
	v_mfma_f32_16x16x32_bf16 v[92:95], v[136:139], v[172:175], v[92:95]
	v_mfma_f32_16x16x32_bf16 v[88:91], v[144:147], v[172:175], v[88:91]
	v_mfma_f32_16x16x32_bf16 v[76:79], v[136:139], v[180:183], v[76:79]
	v_mfma_f32_16x16x32_bf16 v[72:75], v[144:147], v[180:183], v[72:75]
	v_mfma_f32_16x16x32_bf16 v[124:127], v[140:143], v[160:163], v[124:127]
	v_mfma_f32_16x16x32_bf16 v[120:123], v[148:151], v[160:163], v[120:123]
	v_mfma_f32_16x16x32_bf16 v[108:111], v[140:143], v[168:171], v[108:111]
	v_mfma_f32_16x16x32_bf16 v[104:107], v[148:151], v[168:171], v[104:107]
	v_mfma_f32_16x16x32_bf16 v[92:95], v[140:143], v[176:179], v[92:95]
	v_mfma_f32_16x16x32_bf16 v[88:91], v[148:151], v[176:179], v[88:91]
	v_mfma_f32_16x16x32_bf16 v[76:79], v[140:143], v[184:187], v[76:79]
	v_mfma_f32_16x16x32_bf16 v[72:75], v[148:151], v[184:187], v[72:75]
	s_setprio 0
	s_barrier
	s_add_i32 s58, 0, 0x14000
	s_add_i32 s55, s55, s36
	v_add_u32_e32 v152, s58, v134
	v_lshl_add_u64 v[204:205], s[24:25], 0, v[128:129]
	s_mov_b32 m0, s55
	ds_read_b128 v[188:191], v152
	ds_read_b128 v[192:195], v152 offset:1024
	ds_read_b128 v[196:199], v152 offset:2048
	ds_read_b128 v[200:203], v152 offset:3072
	global_load_lds_dwordx4 v[204:205], off
	s_add_i32 m0, s55, 0x2000
	v_lshl_add_u64 v[204:205], s[24:25], 0, v[130:131]
	global_load_lds_dwordx4 v[204:205], off
	s_barrier
	s_waitcnt lgkmcnt(0)
	s_setprio 1
	v_mfma_f32_16x16x32_bf16 v[116:119], v[188:191], v[156:159], v[116:119]
	v_mfma_f32_16x16x32_bf16 v[112:115], v[196:199], v[156:159], v[112:115]
	s_mov_b32 m0, s37
	v_lshl_add_u64 v[204:205], s[28:29], 0, v[128:129]
	v_mfma_f32_16x16x32_bf16 v[100:103], v[188:191], v[164:167], v[100:103]
	v_mfma_f32_16x16x32_bf16 v[96:99], v[196:199], v[164:167], v[96:99]
	v_mfma_f32_16x16x32_bf16 v[84:87], v[188:191], v[172:175], v[84:87]
	v_mfma_f32_16x16x32_bf16 v[80:83], v[196:199], v[172:175], v[80:83]
	v_mfma_f32_16x16x32_bf16 v[68:71], v[188:191], v[180:183], v[68:71]
	v_mfma_f32_16x16x32_bf16 v[64:67], v[196:199], v[180:183], v[64:67]
	v_mfma_f32_16x16x32_bf16 v[116:119], v[192:195], v[160:163], v[116:119]
	v_mfma_f32_16x16x32_bf16 v[112:115], v[200:203], v[160:163], v[112:115]
	v_mfma_f32_16x16x32_bf16 v[100:103], v[192:195], v[168:171], v[100:103]
	v_mfma_f32_16x16x32_bf16 v[96:99], v[200:203], v[168:171], v[96:99]
	v_mfma_f32_16x16x32_bf16 v[84:87], v[192:195], v[176:179], v[84:87]
	v_mfma_f32_16x16x32_bf16 v[80:83], v[200:203], v[176:179], v[80:83]
	v_mfma_f32_16x16x32_bf16 v[68:71], v[192:195], v[184:187], v[68:71]
	v_mfma_f32_16x16x32_bf16 v[64:67], v[200:203], v[184:187], v[64:67]
	s_setprio 0
	s_barrier
	ds_read_b128 v[156:159], v135 offset:16384
	ds_read_b128 v[160:163], v135 offset:17408
	ds_read_b128 v[164:167], v135 offset:18432
	ds_read_b128 v[168:171], v135 offset:19456
	ds_read_b128 v[172:175], v135 offset:20480
	ds_read_b128 v[176:179], v135 offset:21504
	ds_read_b128 v[180:183], v135 offset:22528
	ds_read_b128 v[184:187], v135 offset:23552
	global_load_lds_dwordx4 v[204:205], off
	s_mov_b32 m0, s38
	v_lshl_add_u64 v[204:205], s[28:29], 0, v[130:131]
	global_load_lds_dwordx4 v[204:205], off
	s_barrier
	s_waitcnt lgkmcnt(0)
	s_setprio 1
	v_mfma_f32_16x16x32_bf16 v[60:63], v[136:139], v[156:159], v[60:63]
	v_mfma_f32_16x16x32_bf16 v[56:59], v[144:147], v[156:159], v[56:59]
	v_mfma_f32_16x16x32_bf16 v[44:47], v[136:139], v[164:167], v[44:47]
	v_mfma_f32_16x16x32_bf16 v[40:43], v[144:147], v[164:167], v[40:43]
	v_mfma_f32_16x16x32_bf16 v[28:31], v[136:139], v[172:175], v[28:31]
	v_mfma_f32_16x16x32_bf16 v[24:27], v[144:147], v[172:175], v[24:27]
	v_mfma_f32_16x16x32_bf16 v[12:15], v[136:139], v[180:183], v[12:15]
	v_mfma_f32_16x16x32_bf16 v[8:11], v[144:147], v[180:183], v[8:11]
	v_mfma_f32_16x16x32_bf16 v[60:63], v[140:143], v[160:163], v[60:63]
	v_mfma_f32_16x16x32_bf16 v[56:59], v[148:151], v[160:163], v[56:59]
	v_mfma_f32_16x16x32_bf16 v[44:47], v[140:143], v[168:171], v[44:47]
	v_mfma_f32_16x16x32_bf16 v[40:43], v[148:151], v[168:171], v[40:43]
	v_mfma_f32_16x16x32_bf16 v[28:31], v[140:143], v[176:179], v[28:31]
	v_mfma_f32_16x16x32_bf16 v[24:27], v[148:151], v[176:179], v[24:27]
	v_mfma_f32_16x16x32_bf16 v[12:15], v[140:143], v[184:187], v[12:15]
	v_mfma_f32_16x16x32_bf16 v[8:11], v[148:151], v[184:187], v[8:11]
	s_setprio 0
	s_barrier
; #define PG8_STAGE(bufoff, gbase, voff) do { _Pragma("unroll") for (int _i = 0; _i < 2; ++_i) \
;         __builtin_amdgcn_global_load_lds((const unsigned*)((const char*)(gbase) + (voff)[_i]), (LAS unsigned*)(lds + (bufoff) + ldsw + _i * 8192), 16, 0, 0); } while (0)
; #define PG8_LDA(dst, b, h) do { _Pragma("unroll") for (int m = 0; m < 4; ++m) _Pragma("unroll") for (int k = 0; k < 2; ++k) dst[m][k] = *(const LAS bf16x8*)(lds + PG8_SA(b, h) + aoff + m * 2048 + k * 1024); } while (0)
; #define PG8_LDB(dst, b, h) do { _Pragma("unroll") for (int n = 0; n < 2; ++n) _Pragma("unroll") for (int k = 0; k < 2; ++k) dst[n][k] = *(const LAS bf16x8*)(lds + PG8_SB(b, h) + boff + n * 2048 + k * 1024); } while (0)
; #define PG8_MMA(ai, bj, At, Bt) do { __builtin_amdgcn_s_setprio(1); _Pragma("unroll") for (int m = 0; m < 4; ++m) _Pragma("unroll") for (int n = 0; n < 2; ++n) _Pragma("unroll") for (int k = 0; k < 2; ++k) \
;         acc[ai][bj][m][n] = __builtin_amdgcn_mfma_f32_16x16x32_bf16(Bt[n][k], At[m][k], acc[ai][bj][m][n], 0, 0, 0); __builtin_amdgcn_s_setprio(0); } while (0)
; #define PG8_WAIT_V(n) asm volatile("s_waitcnt vmcnt(" #n ")" ::: "memory")
; #define PG8_WAIT_L(n) asm volatile("s_waitcnt lgkmcnt(" #n ")" ::: "memory")
; #define PG8_BAR __builtin_amdgcn_s_barrier()
; #define PG8_SCHED __builtin_amdgcn_sched_barrier(0)
; template <class Epi>
; __device__ __forceinline__ void gemm_phase(LAS unsigned char* lds, const Gemm g, const StaticOrder& S, const Epi& E) {
;     ...
;             PG8_STAGE(PG8_SB(0, 1), b2 + hstepB, voffB);
;             PG8_WAIT_V(6); PG8_BAR; PG8_MMA(1, 1, At, B1); PG8_BAR;
;             PG8_LDB(B0, 1, 0); PG8_SCHED; PG8_LDA(At, 1, 0); PG8_STAGE(PG8_SA(0, 1), a2 + hstepA, voffA);
;             PG8_WAIT_L(8); PG8_BAR; PG8_WAIT_L(0); PG8_MMA(0, 0, At, B0); PG8_BAR; PG8_SCHED;
;             PG8_LDB(B1, 1, 1); PG8_STAGE(PG8_SB(1, 0), b3, voffB);
;             PG8_BAR; PG8_WAIT_L(0); PG8_MMA(0, 1, At, B1); PG8_BAR;
;             PG8_LDA(At, 1, 1); PG8_STAGE(PG8_SA(1, 0), a3, voffA);
;             PG8_BAR; PG8_WAIT_L(0); PG8_MMA(1, 0, At, B0); PG8_BAR; PG8_SCHED;
	s_add_u32 s56, s24, 0x80000
	s_addc_u32 s57, s25, 0
	s_add_i32 s55, s58, s36
	s_mov_b32 m0, s55
	v_lshl_add_u64 v[136:137], s[56:57], 0, v[128:129]
	global_load_lds_dwordx4 v[136:137], off
	s_add_i32 m0, s55, 0x2000
	v_lshl_add_u64 v[136:137], s[56:57], 0, v[130:131]
	global_load_lds_dwordx4 v[136:137], off
	s_waitcnt vmcnt(6)
	s_barrier
	s_setprio 1
	v_mfma_f32_16x16x32_bf16 v[52:55], v[188:191], v[156:159], v[52:55]
	v_mfma_f32_16x16x32_bf16 v[48:51], v[196:199], v[156:159], v[48:51]
	s_add_i32 s55, 0, 0x18000
	v_add_u32_e32 v148, s55, v134
	v_mfma_f32_16x16x32_bf16 v[36:39], v[188:191], v[164:167], v[36:39]
	v_mfma_f32_16x16x32_bf16 v[32:35], v[196:199], v[164:167], v[32:35]
	v_mfma_f32_16x16x32_bf16 v[20:23], v[188:191], v[172:175], v[20:23]
	v_mfma_f32_16x16x32_bf16 v[16:19], v[196:199], v[172:175], v[16:19]
	v_mfma_f32_16x16x32_bf16 v[4:7], v[188:191], v[180:183], v[4:7]
	v_mfma_f32_16x16x32_bf16 v[0:3], v[196:199], v[180:183], v[0:3]
	v_mfma_f32_16x16x32_bf16 v[52:55], v[192:195], v[160:163], v[52:55]
	v_mfma_f32_16x16x32_bf16 v[48:51], v[200:203], v[160:163], v[48:51]
	v_mfma_f32_16x16x32_bf16 v[36:39], v[192:195], v[168:171], v[36:39]
	v_mfma_f32_16x16x32_bf16 v[32:35], v[200:203], v[168:171], v[32:35]
	v_mfma_f32_16x16x32_bf16 v[20:23], v[192:195], v[176:179], v[20:23]
	v_mfma_f32_16x16x32_bf16 v[16:19], v[200:203], v[176:179], v[16:19]
	v_mfma_f32_16x16x32_bf16 v[4:7], v[192:195], v[184:187], v[4:7]
	v_mfma_f32_16x16x32_bf16 v[0:3], v[200:203], v[184:187], v[0:3]
	s_setprio 0
	s_barrier
	ds_read_b128 v[136:139], v148
	ds_read_b128 v[140:143], v148 offset:1024
	ds_read_b128 v[144:147], v148 offset:2048
	ds_read_b128 v[148:151], v148 offset:3072
	s_add_u32 s28, s28, 0x80000
	s_addc_u32 s29, s29, 0
	s_mov_b32 m0, s39
	v_lshl_add_u64 v[188:189], s[28:29], 0, v[128:129]
	ds_read_b128 v[156:159], v135 offset:32768
	ds_read_b128 v[160:163], v135 offset:33792
	ds_read_b128 v[164:167], v135 offset:34816
	ds_read_b128 v[168:171], v135 offset:35840
	ds_read_b128 v[172:175], v135 offset:36864
	ds_read_b128 v[176:179], v135 offset:37888
	ds_read_b128 v[180:183], v135 offset:38912
	ds_read_b128 v[184:187], v135 offset:39936
	global_load_lds_dwordx4 v[188:189], off
	s_mov_b32 m0, s40
	v_lshl_add_u64 v[188:189], s[28:29], 0, v[130:131]
	global_load_lds_dwordx4 v[188:189], off
	s_waitcnt lgkmcnt(8)
	s_barrier
	s_waitcnt lgkmcnt(0)
	s_setprio 1
	v_mfma_f32_16x16x32_bf16 v[124:127], v[136:139], v[156:159], v[124:127]
	v_mfma_f32_16x16x32_bf16 v[120:123], v[144:147], v[156:159], v[120:123]
	v_mfma_f32_16x16x32_bf16 v[108:111], v[136:139], v[164:167], v[108:111]
	v_mfma_f32_16x16x32_bf16 v[104:107], v[144:147], v[164:167], v[104:107]
	v_mfma_f32_16x16x32_bf16 v[92:95], v[136:139], v[172:175], v[92:95]
	v_mfma_f32_16x16x32_bf16 v[88:91], v[144:147], v[172:175], v[88:91]
	v_mfma_f32_16x16x32_bf16 v[76:79], v[136:139], v[180:183], v[76:79]
	v_mfma_f32_16x16x32_bf16 v[72:75], v[144:147], v[180:183], v[72:75]
	v_mfma_f32_16x16x32_bf16 v[124:127], v[140:143], v[160:163], v[124:127]
	v_mfma_f32_16x16x32_bf16 v[120:123], v[148:151], v[160:163], v[120:123]
	v_mfma_f32_16x16x32_bf16 v[108:111], v[140:143], v[168:171], v[108:111]
	v_mfma_f32_16x16x32_bf16 v[104:107], v[148:151], v[168:171], v[104:107]
	v_mfma_f32_16x16x32_bf16 v[92:95], v[140:143], v[176:179], v[92:95]
	v_mfma_f32_16x16x32_bf16 v[88:91], v[148:151], v[176:179], v[88:91]
	v_mfma_f32_16x16x32_bf16 v[76:79], v[140:143], v[184:187], v[76:79]
	v_mfma_f32_16x16x32_bf16 v[72:75], v[148:151], v[184:187], v[72:75]
	s_setprio 0
	s_barrier
	s_add_i32 s56, 0, 0x1c000
	s_add_u32 s28, s24, 0x4000
	s_addc_u32 s29, s25, 0
	s_add_i32 s55, s55, s36
	v_add_u32_e32 v152, s56, v134
	v_lshl_add_u64 v[204:205], s[28:29], 0, v[128:129]
	s_mov_b32 m0, s55
	ds_read_b128 v[188:191], v152
	ds_read_b128 v[192:195], v152 offset:1024
	ds_read_b128 v[196:199], v152 offset:2048
	ds_read_b128 v[200:203], v152 offset:3072
	global_load_lds_dwordx4 v[204:205], off
	s_add_i32 m0, s55, 0x2000
	v_lshl_add_u64 v[204:205], s[28:29], 0, v[130:131]
	global_load_lds_dwordx4 v[204:205], off
	s_barrier
	s_waitcnt lgkmcnt(0)
	s_setprio 1
	v_mfma_f32_16x16x32_bf16 v[116:119], v[188:191], v[156:159], v[116:119]
	v_mfma_f32_16x16x32_bf16 v[112:115], v[196:199], v[156:159], v[112:115]
	s_mov_b32 m0, s43
	v_lshl_add_u64 v[204:205], s[26:27], 0, v[128:129]
	v_mfma_f32_16x16x32_bf16 v[100:103], v[188:191], v[164:167], v[100:103]
	v_mfma_f32_16x16x32_bf16 v[96:99], v[196:199], v[164:167], v[96:99]
	v_mfma_f32_16x16x32_bf16 v[84:87], v[188:191], v[172:175], v[84:87]
	v_mfma_f32_16x16x32_bf16 v[80:83], v[196:199], v[172:175], v[80:83]
	v_mfma_f32_16x16x32_bf16 v[68:71], v[188:191], v[180:183], v[68:71]
	v_mfma_f32_16x16x32_bf16 v[64:67], v[196:199], v[180:183], v[64:67]
	v_mfma_f32_16x16x32_bf16 v[116:119], v[192:195], v[160:163], v[116:119]
	v_mfma_f32_16x16x32_bf16 v[112:115], v[200:203], v[160:163], v[112:115]
	v_mfma_f32_16x16x32_bf16 v[100:103], v[192:195], v[168:171], v[100:103]
	v_mfma_f32_16x16x32_bf16 v[96:99], v[200:203], v[168:171], v[96:99]
	v_mfma_f32_16x16x32_bf16 v[84:87], v[192:195], v[176:179], v[84:87]
	v_mfma_f32_16x16x32_bf16 v[80:83], v[200:203], v[176:179], v[80:83]
	v_mfma_f32_16x16x32_bf16 v[68:71], v[192:195], v[184:187], v[68:71]
	v_mfma_f32_16x16x32_bf16 v[64:67], v[200:203], v[184:187], v[64:67]
	s_setprio 0
	s_barrier
	ds_read_b128 v[156:159], v135 offset:49152
	ds_read_b128 v[160:163], v135 offset:50176
	ds_read_b128 v[164:167], v135 offset:51200
	ds_read_b128 v[168:171], v135 offset:52224
	ds_read_b128 v[172:175], v135 offset:53248
	ds_read_b128 v[176:179], v135 offset:54272
	ds_read_b128 v[180:183], v135 offset:55296
	ds_read_b128 v[184:187], v135 offset:56320
	global_load_lds_dwordx4 v[204:205], off
	s_mov_b32 m0, s44
	v_lshl_add_u64 v[204:205], s[26:27], 0, v[130:131]
	global_load_lds_dwordx4 v[204:205], off
	s_barrier
; __device__ __forceinline__ unsigned cvt_pk_bf16(float lo, float hi) { unsigned r; asm volatile("v_cvt_pk_bf16_f32 %0, %1, %2" : "=v"(r) : "v"(lo), "v"(hi)); return r; }
; #define PG8_STAGE(bufoff, gbase, voff) do { _Pragma("unroll") for (int _i = 0; _i < 2; ++_i) \
;         __builtin_amdgcn_global_load_lds((const unsigned*)((const char*)(gbase) + (voff)[_i]), (LAS unsigned*)(lds + (bufoff) + ldsw + _i * 8192), 16, 0, 0); } while (0)
; #define PG8_MMA(ai, bj, At, Bt) do { __builtin_amdgcn_s_setprio(1); _Pragma("unroll") for (int m = 0; m < 4; ++m) _Pragma("unroll") for (int n = 0; n < 2; ++n) _Pragma("unroll") for (int k = 0; k < 2; ++k) \
;         acc[ai][bj][m][n] = __builtin_amdgcn_mfma_f32_16x16x32_bf16(Bt[n][k], At[m][k], acc[ai][bj][m][n], 0, 0, 0); __builtin_amdgcn_s_setprio(0); } while (0)
; #define PG8_WAIT_V(n) asm volatile("s_waitcnt vmcnt(" #n ")" ::: "memory")
; #define PG8_WAIT_L(n) asm volatile("s_waitcnt lgkmcnt(" #n ")" ::: "memory")
; #define PG8_BAR __builtin_amdgcn_s_barrier()
; #define PG8_SCHED __builtin_amdgcn_sched_barrier(0)
; template <class Epi>
; __device__ __forceinline__ void gemm_phase(LAS unsigned char* lds, const Gemm g, const StaticOrder& S, const Epi& E) {
;     ...
;             PG8_BAR; PG8_WAIT_L(0); PG8_MMA(1, 0, At, B0); PG8_BAR; PG8_SCHED;
;             PG8_STAGE(PG8_SB(1, 1), b3 + hstepB, voffB);
;             PG8_WAIT_V(6); PG8_BAR; PG8_MMA(1, 1, At, B1); PG8_BAR;
;     __device__ __forceinline__ void operator()(const f32x4 (&acc)[2][2][4][2], const Unit& u, int wr, int wc, int fr, int fq) const {
;         const int row0 = u.pm * BM + wr * 64 + fr, col0 = u.pn * BM + wc * 32 + 8 * fq;
; #pragma unroll
;         for (int ai = 0; ai < 2; ++ai)
; #pragma unroll
;             for (int m = 0; m < 4; ++m) {
;                 const int rowi = row0 + ai * HALF + m * 16;
; #pragma unroll
;                 for (int bj = 0; bj < 2; ++bj) {
;                     f32x4 v0 = acc[ai][bj][m][0], v1 = acc[ai][bj][m][1];
; #pragma unroll
;                     for (int j = 0; j < 4; ++j) { const float a = fmaxf(v0[j], 0.f), b = fmaxf(v1[j], 0.f); v0[j] = a * a; v1[j] = b * b; }
;                     u32x4 w; w.x = cvt_pk_bf16(v0[0], v0[1]); w.y = cvt_pk_bf16(v0[2], v0[3]); w.z = cvt_pk_bf16(v1[0], v1[1]); w.w = cvt_pk_bf16(v1[2], v1[3]);
;                     *(u32x4*)(O + tiled_off(rowi, col0 + bj * HALF, DFF / 64)) = w;
	s_waitcnt lgkmcnt(0)
	s_setprio 1
	v_mfma_f32_16x16x32_bf16 v[60:63], v[136:139], v[156:159], v[60:63]
	v_mfma_f32_16x16x32_bf16 v[56:59], v[144:147], v[156:159], v[56:59]
	v_mfma_f32_16x16x32_bf16 v[44:47], v[136:139], v[164:167], v[44:47]
	v_mfma_f32_16x16x32_bf16 v[40:43], v[144:147], v[164:167], v[40:43]
	v_mfma_f32_16x16x32_bf16 v[28:31], v[136:139], v[172:175], v[28:31]
	v_mfma_f32_16x16x32_bf16 v[24:27], v[144:147], v[172:175], v[24:27]
	v_mfma_f32_16x16x32_bf16 v[12:15], v[136:139], v[180:183], v[12:15]
	v_mfma_f32_16x16x32_bf16 v[8:11], v[144:147], v[180:183], v[8:11]
	v_mfma_f32_16x16x32_bf16 v[60:63], v[140:143], v[160:163], v[60:63]
	v_mfma_f32_16x16x32_bf16 v[56:59], v[148:151], v[160:163], v[56:59]
	v_mfma_f32_16x16x32_bf16 v[44:47], v[140:143], v[168:171], v[44:47]
	v_mfma_f32_16x16x32_bf16 v[40:43], v[148:151], v[168:171], v[40:43]
	v_mfma_f32_16x16x32_bf16 v[28:31], v[140:143], v[176:179], v[28:31]
	v_mfma_f32_16x16x32_bf16 v[24:27], v[148:151], v[176:179], v[24:27]
	v_mfma_f32_16x16x32_bf16 v[12:15], v[140:143], v[184:187], v[12:15]
	v_mfma_f32_16x16x32_bf16 v[8:11], v[148:151], v[184:187], v[8:11]
	s_setprio 0
	s_barrier
	s_add_u32 s24, s24, 0x84000
	s_addc_u32 s25, s25, 0
	s_add_i32 s26, s56, s36
	s_mov_b32 m0, s26
	v_lshl_add_u64 v[136:137], s[24:25], 0, v[128:129]
	global_load_lds_dwordx4 v[136:137], off
	s_add_i32 m0, s26, 0x2000
	v_lshl_add_u64 v[136:137], s[24:25], 0, v[130:131]
	global_load_lds_dwordx4 v[136:137], off
	s_waitcnt vmcnt(6)
	s_barrier
	s_setprio 1
	v_mfma_f32_16x16x32_bf16 v[52:55], v[188:191], v[156:159], v[52:55]
	v_mfma_f32_16x16x32_bf16 v[48:51], v[196:199], v[156:159], v[48:51]
	s_add_i32 s54, s54, 2
	s_add_u32 s22, s22, 0x8000
	s_addc_u32 s23, s23, 0
	s_add_u32 s51, s51, 0x8000
	s_addc_u32 s52, s52, 0
	v_mfma_f32_16x16x32_bf16 v[36:39], v[188:191], v[164:167], v[36:39]
	v_mfma_f32_16x16x32_bf16 v[32:35], v[196:199], v[164:167], v[32:35]
	v_mfma_f32_16x16x32_bf16 v[20:23], v[188:191], v[172:175], v[20:23]
	v_mfma_f32_16x16x32_bf16 v[16:19], v[196:199], v[172:175], v[16:19]
	v_mfma_f32_16x16x32_bf16 v[4:7], v[188:191], v[180:183], v[4:7]
	v_mfma_f32_16x16x32_bf16 v[0:3], v[196:199], v[180:183], v[0:3]
	v_mfma_f32_16x16x32_bf16 v[52:55], v[192:195], v[160:163], v[52:55]
	v_mfma_f32_16x16x32_bf16 v[48:51], v[200:203], v[160:163], v[48:51]
	v_mfma_f32_16x16x32_bf16 v[36:39], v[192:195], v[168:171], v[36:39]
	v_mfma_f32_16x16x32_bf16 v[32:35], v[200:203], v[168:171], v[32:35]
	v_mfma_f32_16x16x32_bf16 v[20:23], v[192:195], v[176:179], v[20:23]
	v_mfma_f32_16x16x32_bf16 v[16:19], v[200:203], v[176:179], v[16:19]
	v_mfma_f32_16x16x32_bf16 v[4:7], v[192:195], v[184:187], v[4:7]
	v_mfma_f32_16x16x32_bf16 v[0:3], v[200:203], v[184:187], v[0:3]
	s_setprio 0
	s_cmp_gt_u32 s54, 29
	s_barrier
	s_cbranch_scc0 .LBB0_141
	s_lshl_b32 s24, s20, 8
	s_lshl_b32 s5, s21, 8
	s_add_i32 s24, s24, s41
	s_or_b32 s5, s5, s42
	s_and_b32 s22, s24, 0xffffff80
	s_ashr_i32 s5, s5, 6
	s_add_i32 s20, s22, s5
	s_ashr_i32 s21, s20, 31
	v_max_f32_e32 v120, 0, v120
	s_lshl_b64 s[20:21], s[20:21], 14
	v_readlane_b32 s26, v252, 57
	v_or_b32_e32 v136, s24, v132
	v_mul_f32_e32 v140, v120, v120
	v_max_f32_e32 v121, 0, v121
	v_max_f32_e32 v122, 0, v122
	v_readlane_b32 s27, v252, 58
	s_add_u32 s20, s26, s20
	v_lshlrev_b32_e32 v137, 6, v136
	s_movk_i32 s28, 0x3c0
	v_lshlrev_b32_e32 v138, 2, v136
	v_max_f32_e32 v120, 0, v125
	v_mul_f32_e32 v125, v121, v121
	v_max_f32_e32 v121, v126, v126
	v_mul_f32_e32 v126, v122, v122
	s_addc_u32 s21, s27, s21
	s_or_b32 s15, s5, 2
	v_and_or_b32 v137, v137, s28, v133
	v_and_b32_e32 v138, 32, v138
	v_max_f32_e32 v124, 0, v124
	v_mul_f32_e32 v120, v120, v120
	v_max_f32_e32 v121, 0, v121
	v_max_f32_e32 v122, 0, v127
	v_max_f32_e32 v123, 0, v123
	s_add_i32 s22, s15, s22
	v_bitop3_b32 v139, v137, s46, v138 bitop3:0xde
	v_mul_f32_e32 v124, v124, v124
	v_mul_f32_e32 v121, v121, v121
	v_mul_f32_e32 v122, v122, v122
	v_mul_f32_e32 v123, v123, v123
	v_cvt_pk_bf16_f32 v120, v124, v120
	v_max_f32_e32 v112, 0, v112
	v_max_f32_e32 v113, 0, v113
	s_ashr_i32 s23, s22, 31
	v_cvt_pk_bf16_f32 v121, v121, v122
	v_cvt_pk_bf16_f32 v122, v140, v125
	v_cvt_pk_bf16_f32 v123, v126, v123
	global_store_dwordx4 v139, v[120:123], s[20:21]
	v_max_f32_e32 v114, 0, v114
	s_lshl_b64 s[22:23], s[22:23], 14
	v_mul_f32_e32 v120, v112, v112
	v_max_f32_e32 v112, v117, v117
	v_mul_f32_e32 v117, v113, v113
	v_max_f32_e32 v112, 0, v112
	v_max_f32_e32 v113, 0, v118
	v_mul_f32_e32 v118, v114, v114
	s_add_u32 s22, s26, s22
	v_max_f32_e32 v116, 0, v116
	v_mul_f32_e32 v112, v112, v112
	v_mul_f32_e32 v113, v113, v113
	v_max_f32_e32 v114, 0, v119
	v_max_f32_e32 v115, 0, v115
	s_addc_u32 s23, s27, s23
	s_or_b32 s25, s24, 16
	v_mul_f32_e32 v116, v116, v116
	v_mul_f32_e32 v114, v114, v114
	v_mul_f32_e32 v115, v115, v115
	v_cvt_pk_bf16_f32 v112, v116, v112
	v_cvt_pk_bf16_f32 v113, v113, v114
	s_lshr_b32 s25, s25, 3
	v_max_f32_e32 v104, 0, v104
	v_cvt_pk_bf16_f32 v114, v120, v117
	v_cvt_pk_bf16_f32 v115, v118, v115
	global_store_dwordx4 v139, v[112:115], s[22:23]
	s_and_b32 s25, s25, 10
	v_max_f32_e32 v105, 0, v105
	v_mul_f32_e32 v113, v104, v104
	v_max_f32_e32 v106, 0, v106
	s_or_b32 s25, s25, s45
	v_max_f32_e32 v104, 0, v109
	v_mul_f32_e32 v109, v105, v105
	v_max_f32_e32 v105, v110, v110
	v_mul_f32_e32 v110, v106, v106
	s_lshl_b32 s25, s25, 10
	v_max_f32_e32 v108, 0, v108
	v_mul_f32_e32 v104, v104, v104
	v_max_f32_e32 v105, 0, v105
	v_max_f32_e32 v106, 0, v111
	v_max_f32_e32 v107, 0, v107
	v_bitop3_b32 v112, v137, s25, v138 bitop3:0xde
	v_mul_f32_e32 v108, v108, v108
	v_mul_f32_e32 v105, v105, v105
	v_mul_f32_e32 v106, v106, v106
	v_mul_f32_e32 v107, v107, v107
; __device__ __forceinline__ unsigned cvt_pk_bf16(float lo, float hi) { unsigned r; asm volatile("v_cvt_pk_bf16_f32 %0, %1, %2" : "=v"(r) : "v"(lo), "v"(hi)); return r; }
;     __device__ __forceinline__ void operator()(const f32x4 (&acc)[2][2][4][2], const Unit& u, int wr, int wc, int fr, int fq) const {
;     ...
;         for (int ai = 0; ai < 2; ++ai)
; #pragma unroll
;             for (int m = 0; m < 4; ++m) {
;                 const int rowi = row0 + ai * HALF + m * 16;
; #pragma unroll
;                 for (int bj = 0; bj < 2; ++bj) {
;                     f32x4 v0 = acc[ai][bj][m][0], v1 = acc[ai][bj][m][1];
; #pragma unroll
;                     for (int j = 0; j < 4; ++j) { const float a = fmaxf(v0[j], 0.f), b = fmaxf(v1[j], 0.f); v0[j] = a * a; v1[j] = b * b; }
;                     u32x4 w; w.x = cvt_pk_bf16(v0[0], v0[1]); w.y = cvt_pk_bf16(v0[2], v0[3]); w.z = cvt_pk_bf16(v1[0], v1[1]); w.w = cvt_pk_bf16(v1[2], v1[3]);
;                     *(u32x4*)(O + tiled_off(rowi, col0 + bj * HALF, DFF / 64)) = w;
;                 }
	v_cvt_pk_bf16_f32 v104, v108, v104
	v_max_f32_e32 v96, 0, v96
	v_max_f32_e32 v97, 0, v97
	v_cvt_pk_bf16_f32 v105, v105, v106
	v_cvt_pk_bf16_f32 v106, v113, v109
	v_cvt_pk_bf16_f32 v107, v110, v107
	global_store_dwordx4 v112, v[104:107], s[20:21]
	s_nop 0
	v_max_f32_e32 v98, 0, v98
	v_mul_f32_e32 v104, v96, v96
	v_max_f32_e32 v96, v101, v101
	v_mul_f32_e32 v101, v97, v97
	v_max_f32_e32 v96, 0, v96
	v_max_f32_e32 v97, 0, v102
	v_mul_f32_e32 v102, v98, v98
	v_max_f32_e32 v100, 0, v100
	v_mul_f32_e32 v96, v96, v96
	v_mul_f32_e32 v97, v97, v97
	v_max_f32_e32 v98, 0, v103
	v_max_f32_e32 v99, 0, v99
	s_or_b32 s25, s24, 32
	v_mul_f32_e32 v100, v100, v100
	v_mul_f32_e32 v98, v98, v98
	v_mul_f32_e32 v99, v99, v99
	v_cvt_pk_bf16_f32 v96, v100, v96
	v_cvt_pk_bf16_f32 v97, v97, v98
	s_lshr_b32 s25, s25, 3
	v_max_f32_e32 v88, 0, v88
	v_cvt_pk_bf16_f32 v98, v104, v101
	v_cvt_pk_bf16_f32 v99, v102, v99
	global_store_dwordx4 v112, v[96:99], s[22:23]
	s_and_b32 s25, s25, 12
	v_max_f32_e32 v89, 0, v89
	v_mul_f32_e32 v97, v88, v88
	v_max_f32_e32 v90, 0, v90
	s_or_b32 s25, s25, s45
	v_max_f32_e32 v88, 0, v93
	v_mul_f32_e32 v93, v89, v89
	v_max_f32_e32 v89, v94, v94
	v_mul_f32_e32 v94, v90, v90
	s_lshl_b32 s25, s25, 10
	v_max_f32_e32 v92, 0, v92
	v_mul_f32_e32 v88, v88, v88
	v_max_f32_e32 v89, 0, v89
	v_max_f32_e32 v90, 0, v95
	v_max_f32_e32 v91, 0, v91
	v_bitop3_b32 v96, v137, s25, v138 bitop3:0xde
	v_mul_f32_e32 v92, v92, v92
	v_mul_f32_e32 v89, v89, v89
	v_mul_f32_e32 v90, v90, v90
	v_mul_f32_e32 v91, v91, v91
	v_cvt_pk_bf16_f32 v88, v92, v88
	v_max_f32_e32 v80, 0, v80
	v_max_f32_e32 v81, 0, v81
	v_cvt_pk_bf16_f32 v89, v89, v90
	v_cvt_pk_bf16_f32 v90, v97, v93
	v_cvt_pk_bf16_f32 v91, v94, v91
	global_store_dwordx4 v96, v[88:91], s[20:21]
	s_nop 0
	v_max_f32_e32 v82, 0, v82
	v_mul_f32_e32 v88, v80, v80
	v_max_f32_e32 v80, v85, v85
	v_mul_f32_e32 v85, v81, v81
	v_max_f32_e32 v80, 0, v80
	v_max_f32_e32 v81, 0, v86
	v_mul_f32_e32 v86, v82, v82
	v_max_f32_e32 v84, 0, v84
	v_mul_f32_e32 v80, v80, v80
	v_mul_f32_e32 v81, v81, v81
	v_max_f32_e32 v82, 0, v87
	v_max_f32_e32 v83, 0, v83
	s_or_b32 s24, s24, 48
	v_mul_f32_e32 v84, v84, v84
	v_mul_f32_e32 v82, v82, v82
	v_mul_f32_e32 v83, v83, v83
	v_cvt_pk_bf16_f32 v80, v84, v80
	v_cvt_pk_bf16_f32 v81, v81, v82
	s_lshr_b32 s24, s24, 3
	v_max_f32_e32 v72, 0, v72
	v_cvt_pk_bf16_f32 v82, v88, v85
	v_cvt_pk_bf16_f32 v83, v86, v83
	global_store_dwordx4 v96, v[80:83], s[22:23]
	s_and_b32 s24, s24, 14
	v_max_f32_e32 v73, 0, v73
	v_mul_f32_e32 v81, v72, v72
	v_max_f32_e32 v74, 0, v74
	s_or_b32 s24, s24, s45
	v_max_f32_e32 v72, 0, v77
	v_mul_f32_e32 v77, v73, v73
	v_max_f32_e32 v73, v78, v78
	v_mul_f32_e32 v78, v74, v74
	s_lshl_b32 s24, s24, 10
	v_max_f32_e32 v76, 0, v76
	v_mul_f32_e32 v72, v72, v72
	v_max_f32_e32 v73, 0, v73
	v_max_f32_e32 v74, 0, v79
	v_max_f32_e32 v75, 0, v75
	v_bitop3_b32 v80, v137, s24, v138 bitop3:0xde
	v_mul_f32_e32 v76, v76, v76
	v_mul_f32_e32 v73, v73, v73
	v_mul_f32_e32 v74, v74, v74
	v_mul_f32_e32 v75, v75, v75
	v_cvt_pk_bf16_f32 v72, v76, v72
	v_max_f32_e32 v64, 0, v64
	v_cvt_pk_bf16_f32 v73, v73, v74
	v_cvt_pk_bf16_f32 v74, v81, v77
	v_cvt_pk_bf16_f32 v75, v78, v75
	global_store_dwordx4 v80, v[72:75], s[20:21]
	v_max_f32_e32 v65, 0, v65
	v_max_f32_e32 v66, 0, v66
	v_mul_f32_e32 v72, v64, v64
	v_max_f32_e32 v64, 0, v69
	v_mul_f32_e32 v69, v65, v65
	v_max_f32_e32 v65, v70, v70
	v_mul_f32_e32 v70, v66, v66
	v_max_f32_e32 v68, 0, v68
	v_mul_f32_e32 v64, v64, v64
	v_max_f32_e32 v65, 0, v65
	v_max_f32_e32 v66, 0, v71
	v_max_f32_e32 v67, 0, v67
	v_mul_f32_e32 v68, v68, v68
	v_mul_f32_e32 v65, v65, v65
	v_mul_f32_e32 v66, v66, v66
	v_mul_f32_e32 v67, v67, v67
	v_cvt_pk_bf16_f32 v64, v68, v64
	v_cvt_pk_bf16_f32 v65, v65, v66
	v_cvt_pk_bf16_f32 v66, v72, v69
	v_cvt_pk_bf16_f32 v67, v70, v67
	global_store_dwordx4 v80, v[64:67], s[22:23]
	s_nop 0
	v_max_f32_e32 v56, 0, v56
	v_add_u32_e32 v64, 0x80, v136
	v_and_b32_e32 v65, 0xffffff80, v64
	v_lshlrev_b32_e32 v66, 6, v64
	v_lshlrev_b32_e32 v64, 2, v64
	v_and_or_b32 v66, v66, s28, v133
	v_and_b32_e32 v64, 32, v64
	v_bitop3_b32 v152, v66, s46, v64 bitop3:0xde
	v_mul_f32_e32 v64, v56, v56
	v_max_f32_e32 v57, 0, v57
	v_max_f32_e32 v58, 0, v58
	v_max_f32_e32 v60, 0, v60
	v_max_f32_e32 v56, 0, v61
	v_mul_f32_e32 v61, v57, v57
	v_max_f32_e32 v57, v62, v62
	v_mul_f32_e32 v62, v58, v58
	v_mul_f32_e32 v60, v60, v60
	v_mul_f32_e32 v56, v56, v56
	v_max_f32_e32 v57, 0, v57
	v_max_f32_e32 v58, 0, v63
	v_mul_f32_e32 v57, v57, v57
	v_mul_f32_e32 v58, v58, v58
	v_cvt_pk_bf16_f32 v56, v60, v56
	v_add_u32_e32 v60, s5, v65
	v_cvt_pk_bf16_f32 v57, v57, v58
	v_cvt_pk_bf16_f32 v58, v64, v61
	v_ashrrev_i32_e32 v61, 31, v60
	v_max_f32_e32 v59, 0, v59
	v_lshlrev_b64 v[60:61], 14, v[60:61]
	v_mul_f32_e32 v59, v59, v59
	v_lshl_add_u64 v[60:61], s[26:27], 0, v[60:61]
	v_cvt_pk_bf16_f32 v59, v62, v59
	v_lshl_add_u64 v[62:63], v[60:61], 0, v[152:153]
	v_max_f32_e32 v48, 0, v48
	global_store_dwordx4 v[62:63], v[56:59], off
	s_nop 0
	v_max_f32_e32 v49, 0, v49
	v_mul_f32_e32 v56, v48, v48
	v_max_f32_e32 v50, 0, v50
	v_max_f32_e32 v52, 0, v52
	v_max_f32_e32 v48, 0, v53
	v_mul_f32_e32 v53, v49, v49
	v_max_f32_e32 v49, v54, v54
	v_mul_f32_e32 v54, v50, v50
	v_mul_f32_e32 v52, v52, v52
	v_mul_f32_e32 v48, v48, v48
	v_max_f32_e32 v49, 0, v49
	v_max_f32_e32 v50, 0, v55
	v_mul_f32_e32 v49, v49, v49
	v_mul_f32_e32 v50, v50, v50
	v_cvt_pk_bf16_f32 v48, v52, v48
	v_add_u32_e32 v52, s15, v65
	v_cvt_pk_bf16_f32 v49, v49, v50
	v_cvt_pk_bf16_f32 v50, v56, v53
	v_ashrrev_i32_e32 v53, 31, v52
	v_max_f32_e32 v51, 0, v51
	v_lshlrev_b64 v[52:53], 14, v[52:53]
	v_mul_f32_e32 v51, v51, v51
; __device__ __forceinline__ unsigned cvt_pk_bf16(float lo, float hi) { unsigned r; asm volatile("v_cvt_pk_bf16_f32 %0, %1, %2" : "=v"(r) : "v"(lo), "v"(hi)); return r; }
; template <class Epi>
; __device__ __forceinline__ void gemm_phase(LAS unsigned char* lds, const Gemm g, const StaticOrder& S, const Epi& E) {
;     ...
;         E(acc, cur, wr, wc, fr, fq);
;         if (!has_next) break;
; #pragma unroll
;         for (int a = 0; a < 2; ++a)
; #pragma unroll
;             for (int b = 0; b < 2; ++b)
; #pragma unroll
;                 for (int m = 0; m < 4; ++m)
; #pragma unroll
;                     for (int n = 0; n < 2; ++n) acc[a][b][m][n] = (f32x4){0.f, 0.f, 0.f, 0.f};
;         cur = nxt; cA = nA; cB = nB; ++ui;
;     __device__ __forceinline__ void operator()(const f32x4 (&acc)[2][2][4][2], const Unit& u, int wr, int wc, int fr, int fq) const {
;     ...
;         for (int ai = 0; ai < 2; ++ai)
; #pragma unroll
;             for (int m = 0; m < 4; ++m) {
;                 const int rowi = row0 + ai * HALF + m * 16;
; #pragma unroll
;                 for (int bj = 0; bj < 2; ++bj) {
;                     f32x4 v0 = acc[ai][bj][m][0], v1 = acc[ai][bj][m][1];
; #pragma unroll
;                     for (int j = 0; j < 4; ++j) { const float a = fmaxf(v0[j], 0.f), b = fmaxf(v1[j], 0.f); v0[j] = a * a; v1[j] = b * b; }
;                     u32x4 w; w.x = cvt_pk_bf16(v0[0], v0[1]); w.y = cvt_pk_bf16(v0[2], v0[3]); w.z = cvt_pk_bf16(v1[0], v1[1]); w.w = cvt_pk_bf16(v1[2], v1[3]);
;                     *(u32x4*)(O + tiled_off(rowi, col0 + bj * HALF, DFF / 64)) = w;
;                 }
	v_lshl_add_u64 v[52:53], s[26:27], 0, v[52:53]
	v_cvt_pk_bf16_f32 v51, v54, v51
	v_lshl_add_u64 v[54:55], v[52:53], 0, v[152:153]
	global_store_dwordx4 v[54:55], v[48:51], off
	s_nop 1
	v_add_u32_e32 v48, 0x90, v136
	v_lshrrev_b32_e32 v49, 3, v48
	v_and_or_b32 v49, v49, 10, s45
	v_lshlrev_b32_e32 v50, 6, v48
	v_lshlrev_b32_e32 v48, 2, v48
	v_and_or_b32 v50, v50, s28, v133
	v_lshlrev_b32_e32 v49, 10, v49
	v_and_b32_e32 v48, 32, v48
	v_max_f32_e32 v40, 0, v40
	v_max_f32_e32 v41, 0, v41
	v_max_f32_e32 v42, 0, v42
	v_bitop3_b32 v152, v50, v49, v48 bitop3:0xde
	v_mul_f32_e32 v48, v40, v40
	v_max_f32_e32 v40, v45, v45
	v_mul_f32_e32 v45, v41, v41
	v_max_f32_e32 v41, v46, v46
	v_mul_f32_e32 v46, v42, v42
	v_max_f32_e32 v44, 0, v44
	v_max_f32_e32 v40, 0, v40
	v_max_f32_e32 v41, 0, v41
	v_max_f32_e32 v42, 0, v47
	v_mul_f32_e32 v44, v44, v44
	v_mul_f32_e32 v40, v40, v40
	v_mul_f32_e32 v41, v41, v41
	v_max_f32_e32 v43, 0, v43
	v_mul_f32_e32 v42, v42, v42
	v_mul_f32_e32 v43, v43, v43
	v_cvt_pk_bf16_f32 v40, v44, v40
	v_cvt_pk_bf16_f32 v41, v41, v42
	v_cvt_pk_bf16_f32 v42, v48, v45
	v_lshl_add_u64 v[44:45], v[60:61], 0, v[152:153]
	v_max_f32_e32 v32, 0, v32
	v_max_f32_e32 v33, 0, v33
	v_max_f32_e32 v34, 0, v34
	v_cvt_pk_bf16_f32 v43, v46, v43
	global_store_dwordx4 v[44:45], v[40:43], off
	s_nop 0
	v_max_f32_e32 v36, 0, v36
	v_mul_f32_e32 v40, v32, v32
	v_max_f32_e32 v32, v37, v37
	v_mul_f32_e32 v37, v33, v33
	v_max_f32_e32 v33, v38, v38
	v_mul_f32_e32 v38, v34, v34
	v_max_f32_e32 v32, 0, v32
	v_max_f32_e32 v33, 0, v33
	v_max_f32_e32 v34, 0, v39
	v_mul_f32_e32 v36, v36, v36
	v_mul_f32_e32 v32, v32, v32
	v_mul_f32_e32 v33, v33, v33
	v_max_f32_e32 v35, 0, v35
	v_mul_f32_e32 v34, v34, v34
	v_mul_f32_e32 v35, v35, v35
	v_cvt_pk_bf16_f32 v32, v36, v32
	v_cvt_pk_bf16_f32 v33, v33, v34
	v_cvt_pk_bf16_f32 v34, v40, v37
	v_lshl_add_u64 v[36:37], v[52:53], 0, v[152:153]
	v_cvt_pk_bf16_f32 v35, v38, v35
	global_store_dwordx4 v[36:37], v[32:35], off
	s_nop 1
	v_add_u32_e32 v32, 0xa0, v136
	v_lshrrev_b32_e32 v33, 3, v32
	v_and_or_b32 v33, v33, 12, s45
	v_lshlrev_b32_e32 v34, 6, v32
	v_lshlrev_b32_e32 v32, 2, v32
	v_and_or_b32 v34, v34, s28, v133
	v_lshlrev_b32_e32 v33, 10, v33
	v_and_b32_e32 v32, 32, v32
	v_max_f32_e32 v24, 0, v24
	v_max_f32_e32 v25, 0, v25
	v_max_f32_e32 v26, 0, v26
	v_bitop3_b32 v152, v34, v33, v32 bitop3:0xde
	v_mul_f32_e32 v32, v24, v24
	v_max_f32_e32 v24, v29, v29
	v_mul_f32_e32 v29, v25, v25
	v_max_f32_e32 v25, v30, v30
	v_mul_f32_e32 v30, v26, v26
	v_max_f32_e32 v28, 0, v28
	v_max_f32_e32 v24, 0, v24
	v_max_f32_e32 v25, 0, v25
	v_max_f32_e32 v26, 0, v31
	v_mul_f32_e32 v28, v28, v28
	v_mul_f32_e32 v24, v24, v24
	v_mul_f32_e32 v25, v25, v25
	v_max_f32_e32 v27, 0, v27
	v_mul_f32_e32 v26, v26, v26
	v_mul_f32_e32 v27, v27, v27
	v_cvt_pk_bf16_f32 v24, v28, v24
	v_cvt_pk_bf16_f32 v25, v25, v26
	v_cvt_pk_bf16_f32 v26, v32, v29
	v_lshl_add_u64 v[28:29], v[60:61], 0, v[152:153]
	v_max_f32_e32 v16, 0, v16
	v_max_f32_e32 v17, 0, v17
	v_max_f32_e32 v18, 0, v18
	v_cvt_pk_bf16_f32 v27, v30, v27
	global_store_dwordx4 v[28:29], v[24:27], off
	s_nop 0
	v_max_f32_e32 v20, 0, v20
	v_mul_f32_e32 v24, v16, v16
	v_max_f32_e32 v16, v21, v21
	v_mul_f32_e32 v21, v17, v17
	v_max_f32_e32 v17, v22, v22
	v_mul_f32_e32 v22, v18, v18
	v_max_f32_e32 v16, 0, v16
	v_max_f32_e32 v17, 0, v17
	v_max_f32_e32 v18, 0, v23
	v_mul_f32_e32 v20, v20, v20
	v_mul_f32_e32 v16, v16, v16
	v_mul_f32_e32 v17, v17, v17
	v_max_f32_e32 v19, 0, v19
	v_mul_f32_e32 v18, v18, v18
	v_mul_f32_e32 v19, v19, v19
	v_cvt_pk_bf16_f32 v16, v20, v16
	v_cvt_pk_bf16_f32 v17, v17, v18
	v_cvt_pk_bf16_f32 v18, v24, v21
	v_lshl_add_u64 v[20:21], v[52:53], 0, v[152:153]
	v_cvt_pk_bf16_f32 v19, v22, v19
	global_store_dwordx4 v[20:21], v[16:19], off
	s_nop 1
	v_add_u32_e32 v16, 0xb0, v136
	v_lshrrev_b32_e32 v17, 3, v16
	v_and_or_b32 v17, v17, 14, s45
	v_lshlrev_b32_e32 v18, 6, v16
	v_lshlrev_b32_e32 v16, 2, v16
	v_and_or_b32 v18, v18, s28, v133
	v_lshlrev_b32_e32 v17, 10, v17
	v_and_b32_e32 v16, 32, v16
	v_max_f32_e32 v8, 0, v8
	v_max_f32_e32 v9, 0, v9
	v_max_f32_e32 v10, 0, v10
	v_bitop3_b32 v152, v18, v17, v16 bitop3:0xde
	v_mul_f32_e32 v16, v8, v8
	v_max_f32_e32 v8, v13, v13
	v_mul_f32_e32 v13, v9, v9
	v_max_f32_e32 v9, v14, v14
	v_mul_f32_e32 v14, v10, v10
	v_max_f32_e32 v12, 0, v12
	v_max_f32_e32 v8, 0, v8
	v_max_f32_e32 v9, 0, v9
	v_max_f32_e32 v10, 0, v15
	v_mul_f32_e32 v12, v12, v12
	v_mul_f32_e32 v8, v8, v8
	v_mul_f32_e32 v9, v9, v9
	v_max_f32_e32 v11, 0, v11
	v_mul_f32_e32 v10, v10, v10
	v_mul_f32_e32 v11, v11, v11
	v_cvt_pk_bf16_f32 v8, v12, v8
	v_cvt_pk_bf16_f32 v9, v9, v10
	v_cvt_pk_bf16_f32 v10, v16, v13
	v_lshl_add_u64 v[12:13], v[60:61], 0, v[152:153]
	v_max_f32_e32 v0, 0, v0
	v_max_f32_e32 v1, 0, v1
	v_max_f32_e32 v2, 0, v2
	v_cvt_pk_bf16_f32 v11, v14, v11
	global_store_dwordx4 v[12:13], v[8:11], off
	s_nop 0
	v_max_f32_e32 v4, 0, v4
	v_mul_f32_e32 v8, v0, v0
	v_max_f32_e32 v0, v5, v5
	v_mul_f32_e32 v5, v1, v1
	v_max_f32_e32 v1, v6, v6
	v_mul_f32_e32 v6, v2, v2
	v_max_f32_e32 v0, 0, v0
	v_max_f32_e32 v1, 0, v1
	v_max_f32_e32 v2, 0, v7
	v_mul_f32_e32 v4, v4, v4
	v_mul_f32_e32 v0, v0, v0
	v_mul_f32_e32 v1, v1, v1
	v_max_f32_e32 v3, 0, v3
	v_mul_f32_e32 v2, v2, v2
	s_mov_b32 s54, 0xd00ab22c
	v_mul_f32_e32 v3, v3, v3
	v_cvt_pk_bf16_f32 v0, v4, v0
	v_cvt_pk_bf16_f32 v1, v1, v2
	v_cvt_pk_bf16_f32 v2, v8, v5
	v_lshl_add_u64 v[4:5], v[52:53], 0, v[152:153]
	s_and_b64 vcc, exec, s[0:1]
	s_mov_b32 s21, s4
	s_mov_b32 s20, s14
	s_mov_b64 s[24:25], s[18:19]
	s_mov_b64 s[22:23], s[16:17]
	s_mov_b32 s55, 0x3febb5fa
	v_cvt_pk_bf16_f32 v3, v6, v3
	global_store_dwordx4 v[4:5], v[0:3], off
	s_cbranch_vccz .LBB0_134
	s_waitcnt vmcnt(0)
	s_cmpk_gt_u32 s31, 0xff
	s_cbranch_scc1 .LBB0_145
	s_barrier

; #define PG8_STAGE(bufoff, gbase, voff) do { _Pragma("unroll") for (int _i = 0; _i < 2; ++_i) \
;         __builtin_amdgcn_global_load_lds((const unsigned*)((const char*)(gbase) + (voff)[_i]), (LAS unsigned*)(lds + (bufoff) + ldsw + _i * 8192), 16, 0, 0); } while (0)
; #define PG8_LDA(dst, b, h) do { _Pragma("unroll") for (int m = 0; m < 4; ++m) _Pragma("unroll") for (int k = 0; k < 2; ++k) dst[m][k] = *(const LAS bf16x8*)(lds + PG8_SA(b, h) + aoff + m * 2048 + k * 1024); } while (0)
; #define PG8_LDB(dst, b, h) do { _Pragma("unroll") for (int n = 0; n < 2; ++n) _Pragma("unroll") for (int k = 0; k < 2; ++k) dst[n][k] = *(const LAS bf16x8*)(lds + PG8_SB(b, h) + boff + n * 2048 + k * 1024); } while (0)
; #define PG8_MMA(ai, bj, At, Bt) do { __builtin_amdgcn_s_setprio(1); _Pragma("unroll") for (int m = 0; m < 4; ++m) _Pragma("unroll") for (int n = 0; n < 2; ++n) _Pragma("unroll") for (int k = 0; k < 2; ++k) \
;         acc[ai][bj][m][n] = __builtin_amdgcn_mfma_f32_16x16x32_bf16(Bt[n][k], At[m][k], acc[ai][bj][m][n], 0, 0, 0); __builtin_amdgcn_s_setprio(0); } while (0)
; #define PG8_WAIT_L(n) asm volatile("s_waitcnt lgkmcnt(" #n ")" ::: "memory")
; #define PG8_BAR __builtin_amdgcn_s_barrier()
; #define PG8_SCHED __builtin_amdgcn_sched_barrier(0)
; template <class Epi>
; __device__ __forceinline__ void gemm_phase(LAS unsigned char* lds, const Gemm g, const StaticOrder& S, const Epi& E) {
;     ...
;             const bool last = (t == nt - 2);
;             const char* a1 = cA + (size_t)(t + 1) * kstep;
;             const char* a2 = last ? nA : cA + (size_t)(t + 2) * kstep; const char* b2 = last ? nB : cB + (size_t)(t + 2) * kstep;
;             const char* a3 = a2 + kstep; const char* b3 = b2 + kstep;
;             PG8_LDB(B0, 0, 0); PG8_SCHED; PG8_LDA(At, 0, 0); PG8_STAGE(PG8_SA(1, 1), a1 + hstepA, voffA);
;             PG8_WAIT_L(8); PG8_BAR; PG8_WAIT_L(0); PG8_MMA(0, 0, At, B0); PG8_BAR; PG8_SCHED;
;             PG8_LDB(B1, 0, 1); PG8_STAGE(PG8_SB(0, 0), b2, voffB);
;             PG8_BAR; PG8_WAIT_L(0); PG8_MMA(0, 1, At, B1); PG8_BAR;
;             PG8_LDA(At, 0, 1); PG8_STAGE(PG8_SA(0, 0), a2, voffA);
;             PG8_BAR; PG8_WAIT_L(0); PG8_MMA(1, 0, At, B0); PG8_BAR; PG8_SCHED;
.LBB0_187:
	s_add_i32 s54, s22, 2
	s_add_u32 s23, s4, 0x4000
	s_addc_u32 s24, s5, 0
	s_cmp_eq_u32 s40, s22
	s_cselect_b32 s26, s6, s23
	s_cselect_b32 s27, s7, s24
	s_cselect_b32 s24, s20, s50
	s_cselect_b32 s25, s21, s51
	s_add_u32 s22, s26, 0x4000
	s_addc_u32 s23, s27, 0
	s_add_i32 s55, 0, 0x10000
	v_add_u32_e32 v140, s55, v207
	ds_read_b128 v[128:131], v140
	ds_read_b128 v[132:135], v140 offset:1024
	ds_read_b128 v[136:139], v140 offset:2048
	ds_read_b128 v[140:143], v140 offset:3072
	v_lshl_add_u64 v[186:187], s[4:5], 0, v[158:159]
	s_add_i32 m0, s33, 0xc000
	ds_read_b128 v[144:147], v209
	ds_read_b128 v[148:151], v209 offset:1024
	ds_read_b128 v[162:165], v209 offset:2048
	ds_read_b128 v[166:169], v209 offset:3072
	ds_read_b128 v[170:173], v209 offset:4096
	ds_read_b128 v[174:177], v209 offset:5120
	ds_read_b128 v[178:181], v209 offset:6144
	ds_read_b128 v[182:185], v209 offset:7168
	global_load_lds_dwordx4 v[186:187], off
	s_add_i32 m0, s33, 0xe000
	v_lshl_add_u64 v[186:187], s[4:5], 0, v[160:161]
	global_load_lds_dwordx4 v[186:187], off
	s_waitcnt lgkmcnt(8)
	s_barrier
	s_waitcnt lgkmcnt(0)
	s_setprio 1
	v_mfma_f32_16x16x32_bf16 v[124:127], v[128:131], v[144:147], v[124:127]
	v_mfma_f32_16x16x32_bf16 v[120:123], v[136:139], v[144:147], v[120:123]
	v_mfma_f32_16x16x32_bf16 v[116:119], v[128:131], v[162:165], v[116:119]
	v_mfma_f32_16x16x32_bf16 v[112:115], v[136:139], v[162:165], v[112:115]
	v_mfma_f32_16x16x32_bf16 v[108:111], v[128:131], v[170:173], v[108:111]
	v_mfma_f32_16x16x32_bf16 v[104:107], v[136:139], v[170:173], v[104:107]
	v_mfma_f32_16x16x32_bf16 v[100:103], v[128:131], v[178:181], v[100:103]
	v_mfma_f32_16x16x32_bf16 v[96:99], v[136:139], v[178:181], v[96:99]
	v_mfma_f32_16x16x32_bf16 v[124:127], v[132:135], v[148:151], v[124:127]
	v_mfma_f32_16x16x32_bf16 v[120:123], v[140:143], v[148:151], v[120:123]
	v_mfma_f32_16x16x32_bf16 v[116:119], v[132:135], v[166:169], v[116:119]
	v_mfma_f32_16x16x32_bf16 v[112:115], v[140:143], v[166:169], v[112:115]
	v_mfma_f32_16x16x32_bf16 v[108:111], v[132:135], v[174:177], v[108:111]
	v_mfma_f32_16x16x32_bf16 v[104:107], v[140:143], v[174:177], v[104:107]
	v_mfma_f32_16x16x32_bf16 v[100:103], v[132:135], v[182:185], v[100:103]
	v_mfma_f32_16x16x32_bf16 v[96:99], v[140:143], v[182:185], v[96:99]
	s_setprio 0
	s_barrier
	s_add_i32 s58, 0, 0x14000
	s_add_i32 s55, s55, s31
	v_add_u32_e32 v198, s58, v207
	v_lshl_add_u64 v[202:203], s[24:25], 0, v[152:153]
	s_mov_b32 m0, s55
	ds_read_b128 v[186:189], v198
	ds_read_b128 v[190:193], v198 offset:1024
	ds_read_b128 v[194:197], v198 offset:2048
	ds_read_b128 v[198:201], v198 offset:3072
	global_load_lds_dwordx4 v[202:203], off
	s_add_i32 m0, s55, 0x2000
	v_lshl_add_u64 v[202:203], s[24:25], 0, v[156:157]
	global_load_lds_dwordx4 v[202:203], off
	s_barrier
	s_waitcnt lgkmcnt(0)
	s_setprio 1
	v_mfma_f32_16x16x32_bf16 v[92:95], v[186:189], v[144:147], v[92:95]
	v_mfma_f32_16x16x32_bf16 v[88:91], v[194:197], v[144:147], v[88:91]
	s_mov_b32 m0, s33
	v_lshl_add_u64 v[202:203], s[26:27], 0, v[152:153]
	v_mfma_f32_16x16x32_bf16 v[84:87], v[186:189], v[162:165], v[84:87]
	v_mfma_f32_16x16x32_bf16 v[80:83], v[194:197], v[162:165], v[80:83]
	v_mfma_f32_16x16x32_bf16 v[76:79], v[186:189], v[170:173], v[76:79]
	v_mfma_f32_16x16x32_bf16 v[72:75], v[194:197], v[170:173], v[72:75]
	v_mfma_f32_16x16x32_bf16 v[68:71], v[186:189], v[178:181], v[68:71]
	v_mfma_f32_16x16x32_bf16 v[64:67], v[194:197], v[178:181], v[64:67]
	v_mfma_f32_16x16x32_bf16 v[92:95], v[190:193], v[148:151], v[92:95]
	v_mfma_f32_16x16x32_bf16 v[88:91], v[198:201], v[148:151], v[88:91]
	v_mfma_f32_16x16x32_bf16 v[84:87], v[190:193], v[166:169], v[84:87]
	v_mfma_f32_16x16x32_bf16 v[80:83], v[198:201], v[166:169], v[80:83]
	v_mfma_f32_16x16x32_bf16 v[76:79], v[190:193], v[174:177], v[76:79]
	v_mfma_f32_16x16x32_bf16 v[72:75], v[198:201], v[174:177], v[72:75]
	v_mfma_f32_16x16x32_bf16 v[68:71], v[190:193], v[182:185], v[68:71]
	v_mfma_f32_16x16x32_bf16 v[64:67], v[198:201], v[182:185], v[64:67]
	s_setprio 0
	s_barrier
	ds_read_b128 v[144:147], v209 offset:16384
	ds_read_b128 v[148:151], v209 offset:17408
	ds_read_b128 v[162:165], v209 offset:18432
	ds_read_b128 v[166:169], v209 offset:19456
	ds_read_b128 v[170:173], v209 offset:20480
	ds_read_b128 v[174:177], v209 offset:21504
	ds_read_b128 v[178:181], v209 offset:22528
	ds_read_b128 v[182:185], v209 offset:23552
	global_load_lds_dwordx4 v[202:203], off
	s_mov_b32 m0, s34
	v_lshl_add_u64 v[202:203], s[26:27], 0, v[156:157]
	global_load_lds_dwordx4 v[202:203], off
	s_barrier
	s_waitcnt lgkmcnt(0)
	s_setprio 1
	v_mfma_f32_16x16x32_bf16 v[60:63], v[128:131], v[144:147], v[60:63]
	v_mfma_f32_16x16x32_bf16 v[56:59], v[136:139], v[144:147], v[56:59]
	v_mfma_f32_16x16x32_bf16 v[52:55], v[128:131], v[162:165], v[52:55]
	v_mfma_f32_16x16x32_bf16 v[48:51], v[136:139], v[162:165], v[48:51]
	v_mfma_f32_16x16x32_bf16 v[44:47], v[128:131], v[170:173], v[44:47]
	v_mfma_f32_16x16x32_bf16 v[40:43], v[136:139], v[170:173], v[40:43]
	v_mfma_f32_16x16x32_bf16 v[36:39], v[128:131], v[178:181], v[36:39]
	v_mfma_f32_16x16x32_bf16 v[32:35], v[136:139], v[178:181], v[32:35]
	v_mfma_f32_16x16x32_bf16 v[60:63], v[132:135], v[148:151], v[60:63]
	v_mfma_f32_16x16x32_bf16 v[56:59], v[140:143], v[148:151], v[56:59]
	v_mfma_f32_16x16x32_bf16 v[52:55], v[132:135], v[166:169], v[52:55]
	v_mfma_f32_16x16x32_bf16 v[48:51], v[140:143], v[166:169], v[48:51]
	v_mfma_f32_16x16x32_bf16 v[44:47], v[132:135], v[174:177], v[44:47]
	v_mfma_f32_16x16x32_bf16 v[40:43], v[140:143], v[174:177], v[40:43]
	v_mfma_f32_16x16x32_bf16 v[36:39], v[132:135], v[182:185], v[36:39]
	v_mfma_f32_16x16x32_bf16 v[32:35], v[140:143], v[182:185], v[32:35]
	s_setprio 0
	s_barrier
; #define PG8_STAGE(bufoff, gbase, voff) do { _Pragma("unroll") for (int _i = 0; _i < 2; ++_i) \
;         __builtin_amdgcn_global_load_lds((const unsigned*)((const char*)(gbase) + (voff)[_i]), (LAS unsigned*)(lds + (bufoff) + ldsw + _i * 8192), 16, 0, 0); } while (0)
; #define PG8_LDA(dst, b, h) do { _Pragma("unroll") for (int m = 0; m < 4; ++m) _Pragma("unroll") for (int k = 0; k < 2; ++k) dst[m][k] = *(const LAS bf16x8*)(lds + PG8_SA(b, h) + aoff + m * 2048 + k * 1024); } while (0)
; #define PG8_LDB(dst, b, h) do { _Pragma("unroll") for (int n = 0; n < 2; ++n) _Pragma("unroll") for (int k = 0; k < 2; ++k) dst[n][k] = *(const LAS bf16x8*)(lds + PG8_SB(b, h) + boff + n * 2048 + k * 1024); } while (0)
; #define PG8_MMA(ai, bj, At, Bt) do { __builtin_amdgcn_s_setprio(1); _Pragma("unroll") for (int m = 0; m < 4; ++m) _Pragma("unroll") for (int n = 0; n < 2; ++n) _Pragma("unroll") for (int k = 0; k < 2; ++k) \
;         acc[ai][bj][m][n] = __builtin_amdgcn_mfma_f32_16x16x32_bf16(Bt[n][k], At[m][k], acc[ai][bj][m][n], 0, 0, 0); __builtin_amdgcn_s_setprio(0); } while (0)
; #define PG8_WAIT_V(n) asm volatile("s_waitcnt vmcnt(" #n ")" ::: "memory")
; #define PG8_WAIT_L(n) asm volatile("s_waitcnt lgkmcnt(" #n ")" ::: "memory")
; #define PG8_BAR __builtin_amdgcn_s_barrier()
; #define PG8_SCHED __builtin_amdgcn_sched_barrier(0)
; template <class Epi>
; __device__ __forceinline__ void gemm_phase(LAS unsigned char* lds, const Gemm g, const StaticOrder& S, const Epi& E) {
;     ...
;             PG8_STAGE(PG8_SB(0, 1), b2 + hstepB, voffB);
;             PG8_WAIT_V(6); PG8_BAR; PG8_MMA(1, 1, At, B1); PG8_BAR;
;             PG8_LDB(B0, 1, 0); PG8_SCHED; PG8_LDA(At, 1, 0); PG8_STAGE(PG8_SA(0, 1), a2 + hstepA, voffA);
;             PG8_WAIT_L(8); PG8_BAR; PG8_WAIT_L(0); PG8_MMA(0, 0, At, B0); PG8_BAR; PG8_SCHED;
;             PG8_LDB(B1, 1, 1); PG8_STAGE(PG8_SB(1, 0), b3, voffB);
;             PG8_BAR; PG8_WAIT_L(0); PG8_MMA(0, 1, At, B1); PG8_BAR;
;             PG8_LDA(At, 1, 1); PG8_STAGE(PG8_SA(1, 0), a3, voffA);
	s_add_u32 s56, s24, s52
	s_addc_u32 s57, s25, 0
	s_add_i32 s55, s58, s31
	s_mov_b32 m0, s55
	v_lshl_add_u64 v[128:129], s[56:57], 0, v[152:153]
	global_load_lds_dwordx4 v[128:129], off
	s_add_i32 m0, s55, 0x2000
	v_lshl_add_u64 v[128:129], s[56:57], 0, v[156:157]
	global_load_lds_dwordx4 v[128:129], off
	s_waitcnt vmcnt(6)
	s_barrier
	s_setprio 1
	v_mfma_f32_16x16x32_bf16 v[28:31], v[186:189], v[144:147], v[28:31]
	v_mfma_f32_16x16x32_bf16 v[24:27], v[194:197], v[144:147], v[24:27]
	s_add_i32 s55, 0, 0x18000
	v_add_u32_e32 v140, s55, v207
	v_mfma_f32_16x16x32_bf16 v[20:23], v[186:189], v[162:165], v[20:23]
	v_mfma_f32_16x16x32_bf16 v[16:19], v[194:197], v[162:165], v[16:19]
	v_mfma_f32_16x16x32_bf16 v[12:15], v[186:189], v[170:173], v[12:15]
	v_mfma_f32_16x16x32_bf16 v[8:11], v[194:197], v[170:173], v[8:11]
	v_mfma_f32_16x16x32_bf16 v[4:7], v[186:189], v[178:181], v[4:7]
	v_mfma_f32_16x16x32_bf16 v[0:3], v[194:197], v[178:181], v[0:3]
	v_mfma_f32_16x16x32_bf16 v[28:31], v[190:193], v[148:151], v[28:31]
	v_mfma_f32_16x16x32_bf16 v[24:27], v[198:201], v[148:151], v[24:27]
	v_mfma_f32_16x16x32_bf16 v[20:23], v[190:193], v[166:169], v[20:23]
	v_mfma_f32_16x16x32_bf16 v[16:19], v[198:201], v[166:169], v[16:19]
	v_mfma_f32_16x16x32_bf16 v[12:15], v[190:193], v[174:177], v[12:15]
	v_mfma_f32_16x16x32_bf16 v[8:11], v[198:201], v[174:177], v[8:11]
	v_mfma_f32_16x16x32_bf16 v[4:7], v[190:193], v[182:185], v[4:7]
	v_mfma_f32_16x16x32_bf16 v[0:3], v[198:201], v[182:185], v[0:3]
	s_setprio 0
	s_barrier
	ds_read_b128 v[128:131], v140
	ds_read_b128 v[132:135], v140 offset:1024
	ds_read_b128 v[136:139], v140 offset:2048
	ds_read_b128 v[140:143], v140 offset:3072
	s_add_u32 s26, s26, s52
	s_addc_u32 s27, s27, 0
	s_mov_b32 m0, s35
	v_lshl_add_u64 v[186:187], s[26:27], 0, v[152:153]
	ds_read_b128 v[144:147], v209 offset:32768
	ds_read_b128 v[148:151], v209 offset:33792
	ds_read_b128 v[162:165], v209 offset:34816
	ds_read_b128 v[166:169], v209 offset:35840
	ds_read_b128 v[170:173], v209 offset:36864
	ds_read_b128 v[174:177], v209 offset:37888
	ds_read_b128 v[178:181], v209 offset:38912
	ds_read_b128 v[182:185], v209 offset:39936
	global_load_lds_dwordx4 v[186:187], off
	s_mov_b32 m0, s36
	v_lshl_add_u64 v[186:187], s[26:27], 0, v[156:157]
	global_load_lds_dwordx4 v[186:187], off
	s_waitcnt lgkmcnt(8)
	s_barrier
	s_waitcnt lgkmcnt(0)
	s_setprio 1
	v_mfma_f32_16x16x32_bf16 v[124:127], v[128:131], v[144:147], v[124:127]
	v_mfma_f32_16x16x32_bf16 v[120:123], v[136:139], v[144:147], v[120:123]
	v_mfma_f32_16x16x32_bf16 v[116:119], v[128:131], v[162:165], v[116:119]
	v_mfma_f32_16x16x32_bf16 v[112:115], v[136:139], v[162:165], v[112:115]
	v_mfma_f32_16x16x32_bf16 v[108:111], v[128:131], v[170:173], v[108:111]
	v_mfma_f32_16x16x32_bf16 v[104:107], v[136:139], v[170:173], v[104:107]
	v_mfma_f32_16x16x32_bf16 v[100:103], v[128:131], v[178:181], v[100:103]
	v_mfma_f32_16x16x32_bf16 v[96:99], v[136:139], v[178:181], v[96:99]
	v_mfma_f32_16x16x32_bf16 v[124:127], v[132:135], v[148:151], v[124:127]
	v_mfma_f32_16x16x32_bf16 v[120:123], v[140:143], v[148:151], v[120:123]
	v_mfma_f32_16x16x32_bf16 v[116:119], v[132:135], v[166:169], v[116:119]
	v_mfma_f32_16x16x32_bf16 v[112:115], v[140:143], v[166:169], v[112:115]
	v_mfma_f32_16x16x32_bf16 v[108:111], v[132:135], v[174:177], v[108:111]
	v_mfma_f32_16x16x32_bf16 v[104:107], v[140:143], v[174:177], v[104:107]
	v_mfma_f32_16x16x32_bf16 v[100:103], v[132:135], v[182:185], v[100:103]
	v_mfma_f32_16x16x32_bf16 v[96:99], v[140:143], v[182:185], v[96:99]
	s_setprio 0
	s_barrier
	s_add_i32 s26, 0, 0x1c000
	s_add_u32 s24, s24, 0x4000
	s_addc_u32 s25, s25, 0
	s_add_i32 s27, s55, s31
	v_add_u32_e32 v198, s26, v207
	v_lshl_add_u64 v[202:203], s[24:25], 0, v[152:153]
	s_mov_b32 m0, s27
	ds_read_b128 v[186:189], v198
	ds_read_b128 v[190:193], v198 offset:1024
	ds_read_b128 v[194:197], v198 offset:2048
	ds_read_b128 v[198:201], v198 offset:3072
	global_load_lds_dwordx4 v[202:203], off
	s_add_i32 m0, s27, 0x2000
	v_lshl_add_u64 v[202:203], s[24:25], 0, v[156:157]
	global_load_lds_dwordx4 v[202:203], off
	s_barrier
; #define PG8_STAGE(bufoff, gbase, voff) do { _Pragma("unroll") for (int _i = 0; _i < 2; ++_i) \
;         __builtin_amdgcn_global_load_lds((const unsigned*)((const char*)(gbase) + (voff)[_i]), (LAS unsigned*)(lds + (bufoff) + ldsw + _i * 8192), 16, 0, 0); } while (0)
; #define PG8_MMA(ai, bj, At, Bt) do { __builtin_amdgcn_s_setprio(1); _Pragma("unroll") for (int m = 0; m < 4; ++m) _Pragma("unroll") for (int n = 0; n < 2; ++n) _Pragma("unroll") for (int k = 0; k < 2; ++k) \
;         acc[ai][bj][m][n] = __builtin_amdgcn_mfma_f32_16x16x32_bf16(Bt[n][k], At[m][k], acc[ai][bj][m][n], 0, 0, 0); __builtin_amdgcn_s_setprio(0); } while (0)
; #define PG8_WAIT_V(n) asm volatile("s_waitcnt vmcnt(" #n ")" ::: "memory")
; #define PG8_WAIT_L(n) asm volatile("s_waitcnt lgkmcnt(" #n ")" ::: "memory")
; #define PG8_BAR __builtin_amdgcn_s_barrier()
; #define PG8_SCHED __builtin_amdgcn_sched_barrier(0)
; template <class Epi>
; __device__ __forceinline__ void gemm_phase(LAS unsigned char* lds, const Gemm g, const StaticOrder& S, const Epi& E) {
;     ...
;             PG8_BAR; PG8_WAIT_L(0); PG8_MMA(1, 0, At, B0); PG8_BAR; PG8_SCHED;
;             PG8_STAGE(PG8_SB(1, 1), b3 + hstepB, voffB);
;             PG8_WAIT_V(6); PG8_BAR; PG8_MMA(1, 1, At, B1); PG8_BAR;
;     __device__ __forceinline__ void operator()(const f32x4 (&acc)[2][2][4][2], const Unit& u, int wr, int wc, int fr, int fq) const {
;         const int row0 = u.pm * BM + wr * 64 + fr, col0 = u.pn * BM + wc * 32 + 8 * fq;
;         const float* gb = gate + (size_t)(row0 >> 12) * (6 * DM);
;         const bool ln = stats != nullptr;
;         constexpr int GB[4] = {0, 4, 8, 16};
;         f32x2 st[4];
; #pragma unroll
;         for (int grp = 0; grp < 3; ++grp) {
;             u32x4 xv[8]; f32x4 cg[2][2], cl[2][2], cb[2][2];
;             if (grp == 0 || grp == 2) {
; #pragma unroll
;                 for (int m = 0; m < 4; ++m) st[m] = ln ? *(const f32x2*)(stats + 2 * (row0 + (grp ? HALF : 0) + m * 16)) : (f32x2){0.f, 1.f};
	s_waitcnt lgkmcnt(0)
	s_setprio 1
	v_mfma_f32_16x16x32_bf16 v[92:95], v[186:189], v[144:147], v[92:95]
	v_mfma_f32_16x16x32_bf16 v[88:91], v[194:197], v[144:147], v[88:91]
	s_mov_b32 m0, s38
	v_lshl_add_u64 v[202:203], s[22:23], 0, v[152:153]
	v_mfma_f32_16x16x32_bf16 v[84:87], v[186:189], v[162:165], v[84:87]
	v_mfma_f32_16x16x32_bf16 v[80:83], v[194:197], v[162:165], v[80:83]
	v_mfma_f32_16x16x32_bf16 v[76:79], v[186:189], v[170:173], v[76:79]
	v_mfma_f32_16x16x32_bf16 v[72:75], v[194:197], v[170:173], v[72:75]
	v_mfma_f32_16x16x32_bf16 v[68:71], v[186:189], v[178:181], v[68:71]
	v_mfma_f32_16x16x32_bf16 v[64:67], v[194:197], v[178:181], v[64:67]
	v_mfma_f32_16x16x32_bf16 v[92:95], v[190:193], v[148:151], v[92:95]
	v_mfma_f32_16x16x32_bf16 v[88:91], v[198:201], v[148:151], v[88:91]
	v_mfma_f32_16x16x32_bf16 v[84:87], v[190:193], v[166:169], v[84:87]
	v_mfma_f32_16x16x32_bf16 v[80:83], v[198:201], v[166:169], v[80:83]
	v_mfma_f32_16x16x32_bf16 v[76:79], v[190:193], v[174:177], v[76:79]
	v_mfma_f32_16x16x32_bf16 v[72:75], v[198:201], v[174:177], v[72:75]
	v_mfma_f32_16x16x32_bf16 v[68:71], v[190:193], v[182:185], v[68:71]
	v_mfma_f32_16x16x32_bf16 v[64:67], v[198:201], v[182:185], v[64:67]
	s_setprio 0
	s_barrier
	ds_read_b128 v[144:147], v209 offset:49152
	ds_read_b128 v[148:151], v209 offset:50176
	ds_read_b128 v[162:165], v209 offset:51200
	ds_read_b128 v[166:169], v209 offset:52224
	ds_read_b128 v[170:173], v209 offset:53248
	ds_read_b128 v[174:177], v209 offset:54272
	ds_read_b128 v[178:181], v209 offset:55296
	ds_read_b128 v[182:185], v209 offset:56320
	global_load_lds_dwordx4 v[202:203], off
	s_mov_b32 m0, s39
	v_lshl_add_u64 v[202:203], s[22:23], 0, v[156:157]
	global_load_lds_dwordx4 v[202:203], off
	s_barrier
	s_waitcnt lgkmcnt(0)
	s_setprio 1
	v_mfma_f32_16x16x32_bf16 v[60:63], v[128:131], v[144:147], v[60:63]
	v_mfma_f32_16x16x32_bf16 v[56:59], v[136:139], v[144:147], v[56:59]
	v_mfma_f32_16x16x32_bf16 v[52:55], v[128:131], v[162:165], v[52:55]
	v_mfma_f32_16x16x32_bf16 v[48:51], v[136:139], v[162:165], v[48:51]
	v_mfma_f32_16x16x32_bf16 v[44:47], v[128:131], v[170:173], v[44:47]
	v_mfma_f32_16x16x32_bf16 v[40:43], v[136:139], v[170:173], v[40:43]
	v_mfma_f32_16x16x32_bf16 v[36:39], v[128:131], v[178:181], v[36:39]
	v_mfma_f32_16x16x32_bf16 v[32:35], v[136:139], v[178:181], v[32:35]
	v_mfma_f32_16x16x32_bf16 v[60:63], v[132:135], v[148:151], v[60:63]
	v_mfma_f32_16x16x32_bf16 v[56:59], v[140:143], v[148:151], v[56:59]
	v_mfma_f32_16x16x32_bf16 v[52:55], v[132:135], v[166:169], v[52:55]
	v_mfma_f32_16x16x32_bf16 v[48:51], v[140:143], v[166:169], v[48:51]
	v_mfma_f32_16x16x32_bf16 v[44:47], v[132:135], v[174:177], v[44:47]
	v_mfma_f32_16x16x32_bf16 v[40:43], v[140:143], v[174:177], v[40:43]
	v_mfma_f32_16x16x32_bf16 v[36:39], v[132:135], v[182:185], v[36:39]
	v_mfma_f32_16x16x32_bf16 v[32:35], v[140:143], v[182:185], v[32:35]
	s_setprio 0
	s_barrier
	s_add_u32 s22, s24, s52
	s_addc_u32 s23, s25, 0
	s_add_i32 s24, s26, s31
	s_mov_b32 m0, s24
	v_lshl_add_u64 v[128:129], s[22:23], 0, v[152:153]
	global_load_lds_dwordx4 v[128:129], off
	s_add_i32 m0, s24, 0x2000
	v_lshl_add_u64 v[128:129], s[22:23], 0, v[156:157]
	global_load_lds_dwordx4 v[128:129], off
	s_waitcnt vmcnt(6)
	s_barrier
	s_setprio 1
	v_mfma_f32_16x16x32_bf16 v[28:31], v[186:189], v[144:147], v[28:31]
	v_mfma_f32_16x16x32_bf16 v[24:27], v[194:197], v[144:147], v[24:27]
	s_add_u32 s4, s4, 0x8000
	s_addc_u32 s5, s5, 0
	s_add_u32 s50, s50, 0x8000
	s_addc_u32 s51, s51, 0
	v_mfma_f32_16x16x32_bf16 v[20:23], v[186:189], v[162:165], v[20:23]
	v_mfma_f32_16x16x32_bf16 v[16:19], v[194:197], v[162:165], v[16:19]
	v_mfma_f32_16x16x32_bf16 v[12:15], v[186:189], v[170:173], v[12:15]
	v_mfma_f32_16x16x32_bf16 v[8:11], v[194:197], v[170:173], v[8:11]
	v_mfma_f32_16x16x32_bf16 v[4:7], v[186:189], v[178:181], v[4:7]
	v_mfma_f32_16x16x32_bf16 v[0:3], v[194:197], v[178:181], v[0:3]
	v_mfma_f32_16x16x32_bf16 v[28:31], v[190:193], v[148:151], v[28:31]
	v_mfma_f32_16x16x32_bf16 v[24:27], v[198:201], v[148:151], v[24:27]
	v_mfma_f32_16x16x32_bf16 v[20:23], v[190:193], v[166:169], v[20:23]
	v_mfma_f32_16x16x32_bf16 v[16:19], v[198:201], v[166:169], v[16:19]
	v_mfma_f32_16x16x32_bf16 v[12:15], v[190:193], v[174:177], v[12:15]
	v_mfma_f32_16x16x32_bf16 v[8:11], v[198:201], v[174:177], v[8:11]
	v_mfma_f32_16x16x32_bf16 v[4:7], v[190:193], v[182:185], v[4:7]
	v_mfma_f32_16x16x32_bf16 v[0:3], v[198:201], v[182:185], v[0:3]
	s_setprio 0
	s_cmp_ge_u32 s54, s28
	s_mov_b32 s22, s54
	s_barrier
	s_cbranch_scc0 .LBB0_187
	s_lshl_b32 s22, s49, 8
	s_add_i32 s22, s22, s37
	v_or_b32_e32 v162, s22, v206
	v_lshlrev_b32_e32 v170, 1, v162
	v_cndmask_b32_e64 v128, 0, 1, s[12:13]
	v_mov_b32_e32 v182, 1.0
	v_mov_b32_e32 v184, 0
	v_cmp_ne_u32_e64 s[4:5], 1, v128
	s_andn2_b64 vcc, exec, s[12:13]
	v_ashrrev_i32_e32 v171, 31, v170
	v_mov_b32_e32 v192, 0
	v_mov_b32_e32 v194, 1.0
	s_cbranch_vccnz .LBB0_190
	v_lshl_add_u64 v[128:129], v[170:171], 2, s[14:15]
	global_load_dwordx2 v[192:193], v[128:129], off
	s_waitcnt vmcnt(0)
	v_mov_b32_e32 v194, v193

; #define PG8_STAGE(bufoff, gbase, voff) do { _Pragma("unroll") for (int _i = 0; _i < 2; ++_i) \
;         __builtin_amdgcn_global_load_lds((const unsigned*)((const char*)(gbase) + (voff)[_i]), (LAS unsigned*)(lds + (bufoff) + ldsw + _i * 8192), 16, 0, 0); } while (0)
; #define PG8_LDA(dst, b, h) do { _Pragma("unroll") for (int m = 0; m < 4; ++m) _Pragma("unroll") for (int k = 0; k < 2; ++k) dst[m][k] = *(const LAS bf16x8*)(lds + PG8_SA(b, h) + aoff + m * 2048 + k * 1024); } while (0)
; #define PG8_LDB(dst, b, h) do { _Pragma("unroll") for (int n = 0; n < 2; ++n) _Pragma("unroll") for (int k = 0; k < 2; ++k) dst[n][k] = *(const LAS bf16x8*)(lds + PG8_SB(b, h) + boff + n * 2048 + k * 1024); } while (0)
; #define PG8_MMA(ai, bj, At, Bt) do { __builtin_amdgcn_s_setprio(1); _Pragma("unroll") for (int m = 0; m < 4; ++m) _Pragma("unroll") for (int n = 0; n < 2; ++n) _Pragma("unroll") for (int k = 0; k < 2; ++k) \
;         acc[ai][bj][m][n] = __builtin_amdgcn_mfma_f32_16x16x32_bf16(Bt[n][k], At[m][k], acc[ai][bj][m][n], 0, 0, 0); __builtin_amdgcn_s_setprio(0); } while (0)
; #define PG8_WAIT_L(n) asm volatile("s_waitcnt lgkmcnt(" #n ")" ::: "memory")
; #define PG8_BAR __builtin_amdgcn_s_barrier()
; #define PG8_SCHED __builtin_amdgcn_sched_barrier(0)
; template <class Epi>
; __device__ __forceinline__ void gemm_phase(LAS unsigned char* lds, const Gemm g, const StaticOrder& S, const Epi& E) {
;     ...
;             const bool last = (t == nt - 2);
;             const char* a1 = cA + (size_t)(t + 1) * kstep;
;             const char* a2 = last ? nA : cA + (size_t)(t + 2) * kstep; const char* b2 = last ? nB : cB + (size_t)(t + 2) * kstep;
;             const char* a3 = a2 + kstep; const char* b3 = b2 + kstep;
;             PG8_LDB(B0, 0, 0); PG8_SCHED; PG8_LDA(At, 0, 0); PG8_STAGE(PG8_SA(1, 1), a1 + hstepA, voffA);
;             PG8_WAIT_L(8); PG8_BAR; PG8_WAIT_L(0); PG8_MMA(0, 0, At, B0); PG8_BAR; PG8_SCHED;
;             PG8_LDB(B1, 0, 1); PG8_STAGE(PG8_SB(0, 0), b2, voffB);
;             PG8_BAR; PG8_WAIT_L(0); PG8_MMA(0, 1, At, B1); PG8_BAR;
;             PG8_LDA(At, 0, 1); PG8_STAGE(PG8_SA(0, 0), a2, voffA);
;             PG8_BAR; PG8_WAIT_L(0); PG8_MMA(1, 0, At, B0); PG8_BAR; PG8_SCHED;
.LBB0_247:
	s_add_u32 s14, s12, 0xfff84000
	s_addc_u32 s15, s13, -1
	s_cmp_eq_u32 s38, 28
	s_cselect_b32 s18, s11, s14
	s_cselect_b32 s19, s5, s15
	s_cselect_b32 s14, s35, s36
	s_cselect_b32 s15, s3, s37
	s_add_u32 s16, s18, 0x4000
	s_addc_u32 s17, s19, 0
	s_add_i32 s39, 0, 0x10000
	v_add_u32_e32 v140, s39, v170
	ds_read_b128 v[128:131], v140
	ds_read_b128 v[132:135], v140 offset:1024
	ds_read_b128 v[136:139], v140 offset:2048
	ds_read_b128 v[140:143], v140 offset:3072
	v_lshl_add_u64 v[194:195], s[12:13], 0, v[156:157]
	s_add_i32 m0, s25, 0xc000
	ds_read_b128 v[144:147], v172
	ds_read_b128 v[148:151], v172 offset:1024
	ds_read_b128 v[166:169], v172 offset:2048
	ds_read_b128 v[174:177], v172 offset:3072
	ds_read_b128 v[178:181], v172 offset:4096
	ds_read_b128 v[182:185], v172 offset:5120
	ds_read_b128 v[186:189], v172 offset:6144
	ds_read_b128 v[190:193], v172 offset:7168
	global_load_lds_dwordx4 v[194:195], off
	s_add_i32 m0, s25, 0xe000
	v_lshl_add_u64 v[194:195], s[12:13], 0, v[158:159]
	global_load_lds_dwordx4 v[194:195], off
	s_waitcnt lgkmcnt(8)
	s_barrier
	s_waitcnt lgkmcnt(0)
	s_setprio 1
	v_mfma_f32_16x16x32_bf16 v[124:127], v[128:131], v[144:147], v[124:127]
	v_mfma_f32_16x16x32_bf16 v[120:123], v[136:139], v[144:147], v[120:123]
	v_mfma_f32_16x16x32_bf16 v[108:111], v[128:131], v[166:169], v[108:111]
	v_mfma_f32_16x16x32_bf16 v[104:107], v[136:139], v[166:169], v[104:107]
	v_mfma_f32_16x16x32_bf16 v[92:95], v[128:131], v[178:181], v[92:95]
	v_mfma_f32_16x16x32_bf16 v[88:91], v[136:139], v[178:181], v[88:91]
	v_mfma_f32_16x16x32_bf16 v[76:79], v[128:131], v[186:189], v[76:79]
	v_mfma_f32_16x16x32_bf16 v[72:75], v[136:139], v[186:189], v[72:75]
	v_mfma_f32_16x16x32_bf16 v[124:127], v[132:135], v[148:151], v[124:127]
	v_mfma_f32_16x16x32_bf16 v[120:123], v[140:143], v[148:151], v[120:123]
	v_mfma_f32_16x16x32_bf16 v[108:111], v[132:135], v[174:177], v[108:111]
	v_mfma_f32_16x16x32_bf16 v[104:107], v[140:143], v[174:177], v[104:107]
	v_mfma_f32_16x16x32_bf16 v[92:95], v[132:135], v[182:185], v[92:95]
	v_mfma_f32_16x16x32_bf16 v[88:91], v[140:143], v[182:185], v[88:91]
	v_mfma_f32_16x16x32_bf16 v[76:79], v[132:135], v[190:193], v[76:79]
	v_mfma_f32_16x16x32_bf16 v[72:75], v[140:143], v[190:193], v[72:75]
	s_setprio 0
	s_barrier
	s_add_i32 s42, 0, 0x14000
	s_add_i32 s39, s39, s23
	v_add_u32_e32 v152, s42, v170
	v_lshl_add_u64 v[210:211], s[14:15], 0, v[156:157]
	s_mov_b32 m0, s39
	ds_read_b128 v[194:197], v152
	ds_read_b128 v[198:201], v152 offset:1024
	ds_read_b128 v[202:205], v152 offset:2048
	ds_read_b128 v[206:209], v152 offset:3072
	global_load_lds_dwordx4 v[210:211], off
	s_add_i32 m0, s39, 0x2000
	v_lshl_add_u64 v[210:211], s[14:15], 0, v[158:159]
	global_load_lds_dwordx4 v[210:211], off
	s_barrier
	s_waitcnt lgkmcnt(0)
	s_setprio 1
	v_mfma_f32_16x16x32_bf16 v[116:119], v[194:197], v[144:147], v[116:119]
	v_mfma_f32_16x16x32_bf16 v[112:115], v[202:205], v[144:147], v[112:115]
	s_mov_b32 m0, s25
	v_lshl_add_u64 v[210:211], s[18:19], 0, v[156:157]
	v_mfma_f32_16x16x32_bf16 v[100:103], v[194:197], v[166:169], v[100:103]
	v_mfma_f32_16x16x32_bf16 v[96:99], v[202:205], v[166:169], v[96:99]
	v_mfma_f32_16x16x32_bf16 v[84:87], v[194:197], v[178:181], v[84:87]
	v_mfma_f32_16x16x32_bf16 v[80:83], v[202:205], v[178:181], v[80:83]
	v_mfma_f32_16x16x32_bf16 v[68:71], v[194:197], v[186:189], v[68:71]
	v_mfma_f32_16x16x32_bf16 v[64:67], v[202:205], v[186:189], v[64:67]
	v_mfma_f32_16x16x32_bf16 v[116:119], v[198:201], v[148:151], v[116:119]
	v_mfma_f32_16x16x32_bf16 v[112:115], v[206:209], v[148:151], v[112:115]
	v_mfma_f32_16x16x32_bf16 v[100:103], v[198:201], v[174:177], v[100:103]
	v_mfma_f32_16x16x32_bf16 v[96:99], v[206:209], v[174:177], v[96:99]
	v_mfma_f32_16x16x32_bf16 v[84:87], v[198:201], v[182:185], v[84:87]
	v_mfma_f32_16x16x32_bf16 v[80:83], v[206:209], v[182:185], v[80:83]
	v_mfma_f32_16x16x32_bf16 v[68:71], v[198:201], v[190:193], v[68:71]
	v_mfma_f32_16x16x32_bf16 v[64:67], v[206:209], v[190:193], v[64:67]
	s_setprio 0
	s_barrier
	ds_read_b128 v[144:147], v172 offset:16384
	ds_read_b128 v[148:151], v172 offset:17408
	ds_read_b128 v[166:169], v172 offset:18432
	ds_read_b128 v[174:177], v172 offset:19456
	ds_read_b128 v[178:181], v172 offset:20480
	ds_read_b128 v[182:185], v172 offset:21504
	ds_read_b128 v[186:189], v172 offset:22528
	ds_read_b128 v[190:193], v172 offset:23552
	global_load_lds_dwordx4 v[210:211], off
	s_mov_b32 m0, s26
	v_lshl_add_u64 v[210:211], s[18:19], 0, v[158:159]
	global_load_lds_dwordx4 v[210:211], off
	s_barrier
	s_waitcnt lgkmcnt(0)
	s_setprio 1
	v_mfma_f32_16x16x32_bf16 v[60:63], v[128:131], v[144:147], v[60:63]
	v_mfma_f32_16x16x32_bf16 v[56:59], v[136:139], v[144:147], v[56:59]
	v_mfma_f32_16x16x32_bf16 v[44:47], v[128:131], v[166:169], v[44:47]
	v_mfma_f32_16x16x32_bf16 v[40:43], v[136:139], v[166:169], v[40:43]
	v_mfma_f32_16x16x32_bf16 v[28:31], v[128:131], v[178:181], v[28:31]
	v_mfma_f32_16x16x32_bf16 v[24:27], v[136:139], v[178:181], v[24:27]
	v_mfma_f32_16x16x32_bf16 v[12:15], v[128:131], v[186:189], v[12:15]
	v_mfma_f32_16x16x32_bf16 v[8:11], v[136:139], v[186:189], v[8:11]
	v_mfma_f32_16x16x32_bf16 v[60:63], v[132:135], v[148:151], v[60:63]
	v_mfma_f32_16x16x32_bf16 v[56:59], v[140:143], v[148:151], v[56:59]
	v_mfma_f32_16x16x32_bf16 v[44:47], v[132:135], v[174:177], v[44:47]
	v_mfma_f32_16x16x32_bf16 v[40:43], v[140:143], v[174:177], v[40:43]
	v_mfma_f32_16x16x32_bf16 v[28:31], v[132:135], v[182:185], v[28:31]
	v_mfma_f32_16x16x32_bf16 v[24:27], v[140:143], v[182:185], v[24:27]
	v_mfma_f32_16x16x32_bf16 v[12:15], v[132:135], v[190:193], v[12:15]
	v_mfma_f32_16x16x32_bf16 v[8:11], v[140:143], v[190:193], v[8:11]
	s_setprio 0
	s_barrier
; #define PG8_STAGE(bufoff, gbase, voff) do { _Pragma("unroll") for (int _i = 0; _i < 2; ++_i) \
;         __builtin_amdgcn_global_load_lds((const unsigned*)((const char*)(gbase) + (voff)[_i]), (LAS unsigned*)(lds + (bufoff) + ldsw + _i * 8192), 16, 0, 0); } while (0)
; #define PG8_LDA(dst, b, h) do { _Pragma("unroll") for (int m = 0; m < 4; ++m) _Pragma("unroll") for (int k = 0; k < 2; ++k) dst[m][k] = *(const LAS bf16x8*)(lds + PG8_SA(b, h) + aoff + m * 2048 + k * 1024); } while (0)
; #define PG8_LDB(dst, b, h) do { _Pragma("unroll") for (int n = 0; n < 2; ++n) _Pragma("unroll") for (int k = 0; k < 2; ++k) dst[n][k] = *(const LAS bf16x8*)(lds + PG8_SB(b, h) + boff + n * 2048 + k * 1024); } while (0)
; #define PG8_MMA(ai, bj, At, Bt) do { __builtin_amdgcn_s_setprio(1); _Pragma("unroll") for (int m = 0; m < 4; ++m) _Pragma("unroll") for (int n = 0; n < 2; ++n) _Pragma("unroll") for (int k = 0; k < 2; ++k) \
;         acc[ai][bj][m][n] = __builtin_amdgcn_mfma_f32_16x16x32_bf16(Bt[n][k], At[m][k], acc[ai][bj][m][n], 0, 0, 0); __builtin_amdgcn_s_setprio(0); } while (0)
; #define PG8_WAIT_V(n) asm volatile("s_waitcnt vmcnt(" #n ")" ::: "memory")
; #define PG8_WAIT_L(n) asm volatile("s_waitcnt lgkmcnt(" #n ")" ::: "memory")
; #define PG8_BAR __builtin_amdgcn_s_barrier()
; #define PG8_SCHED __builtin_amdgcn_sched_barrier(0)
; template <class Epi>
; __device__ __forceinline__ void gemm_phase(LAS unsigned char* lds, const Gemm g, const StaticOrder& S, const Epi& E) {
;     ...
;             PG8_STAGE(PG8_SB(0, 1), b2 + hstepB, voffB);
;             PG8_WAIT_V(6); PG8_BAR; PG8_MMA(1, 1, At, B1); PG8_BAR;
;             PG8_LDB(B0, 1, 0); PG8_SCHED; PG8_LDA(At, 1, 0); PG8_STAGE(PG8_SA(0, 1), a2 + hstepA, voffA);
;             PG8_WAIT_L(8); PG8_BAR; PG8_WAIT_L(0); PG8_MMA(0, 0, At, B0); PG8_BAR; PG8_SCHED;
;             PG8_LDB(B1, 1, 1); PG8_STAGE(PG8_SB(1, 0), b3, voffB);
;             PG8_BAR; PG8_WAIT_L(0); PG8_MMA(0, 1, At, B1); PG8_BAR;
;             PG8_LDA(At, 1, 1); PG8_STAGE(PG8_SA(1, 0), a3, voffA);
;             PG8_BAR; PG8_WAIT_L(0); PG8_MMA(1, 0, At, B0); PG8_BAR; PG8_SCHED;
	s_add_u32 s40, s14, 0x80000
	s_addc_u32 s41, s15, 0
	s_add_i32 s39, s42, s23
	s_mov_b32 m0, s39
	v_lshl_add_u64 v[128:129], s[40:41], 0, v[156:157]
	global_load_lds_dwordx4 v[128:129], off
	s_add_i32 m0, s39, 0x2000
	v_lshl_add_u64 v[128:129], s[40:41], 0, v[158:159]
	global_load_lds_dwordx4 v[128:129], off
	s_waitcnt vmcnt(6)
	s_barrier
	s_setprio 1
	v_mfma_f32_16x16x32_bf16 v[52:55], v[194:197], v[144:147], v[52:55]
	v_mfma_f32_16x16x32_bf16 v[48:51], v[202:205], v[144:147], v[48:51]
	s_add_i32 s39, 0, 0x18000
	v_add_u32_e32 v140, s39, v170
	v_mfma_f32_16x16x32_bf16 v[36:39], v[194:197], v[166:169], v[36:39]
	v_mfma_f32_16x16x32_bf16 v[32:35], v[202:205], v[166:169], v[32:35]
	v_mfma_f32_16x16x32_bf16 v[20:23], v[194:197], v[178:181], v[20:23]
	v_mfma_f32_16x16x32_bf16 v[16:19], v[202:205], v[178:181], v[16:19]
	v_mfma_f32_16x16x32_bf16 v[4:7], v[194:197], v[186:189], v[4:7]
	v_mfma_f32_16x16x32_bf16 v[0:3], v[202:205], v[186:189], v[0:3]
	v_mfma_f32_16x16x32_bf16 v[52:55], v[198:201], v[148:151], v[52:55]
	v_mfma_f32_16x16x32_bf16 v[48:51], v[206:209], v[148:151], v[48:51]
	v_mfma_f32_16x16x32_bf16 v[36:39], v[198:201], v[174:177], v[36:39]
	v_mfma_f32_16x16x32_bf16 v[32:35], v[206:209], v[174:177], v[32:35]
	v_mfma_f32_16x16x32_bf16 v[20:23], v[198:201], v[182:185], v[20:23]
	v_mfma_f32_16x16x32_bf16 v[16:19], v[206:209], v[182:185], v[16:19]
	v_mfma_f32_16x16x32_bf16 v[4:7], v[198:201], v[190:193], v[4:7]
	v_mfma_f32_16x16x32_bf16 v[0:3], v[206:209], v[190:193], v[0:3]
	s_setprio 0
	s_barrier
	ds_read_b128 v[128:131], v140
	ds_read_b128 v[132:135], v140 offset:1024
	ds_read_b128 v[136:139], v140 offset:2048
	ds_read_b128 v[140:143], v140 offset:3072
	s_add_u32 s18, s18, 0x80000
	s_addc_u32 s19, s19, 0
	s_mov_b32 m0, s27
	v_lshl_add_u64 v[194:195], s[18:19], 0, v[156:157]
	ds_read_b128 v[144:147], v172 offset:32768
	ds_read_b128 v[148:151], v172 offset:33792
	ds_read_b128 v[166:169], v172 offset:34816
	ds_read_b128 v[174:177], v172 offset:35840
	ds_read_b128 v[178:181], v172 offset:36864
	ds_read_b128 v[182:185], v172 offset:37888
	ds_read_b128 v[186:189], v172 offset:38912
	ds_read_b128 v[190:193], v172 offset:39936
	global_load_lds_dwordx4 v[194:195], off
	s_mov_b32 m0, s28
	v_lshl_add_u64 v[194:195], s[18:19], 0, v[158:159]
	global_load_lds_dwordx4 v[194:195], off
	s_waitcnt lgkmcnt(8)
	s_barrier
	s_waitcnt lgkmcnt(0)
	s_setprio 1
	v_mfma_f32_16x16x32_bf16 v[124:127], v[128:131], v[144:147], v[124:127]
	v_mfma_f32_16x16x32_bf16 v[120:123], v[136:139], v[144:147], v[120:123]
	v_mfma_f32_16x16x32_bf16 v[108:111], v[128:131], v[166:169], v[108:111]
	v_mfma_f32_16x16x32_bf16 v[104:107], v[136:139], v[166:169], v[104:107]
	v_mfma_f32_16x16x32_bf16 v[92:95], v[128:131], v[178:181], v[92:95]
	v_mfma_f32_16x16x32_bf16 v[88:91], v[136:139], v[178:181], v[88:91]
	v_mfma_f32_16x16x32_bf16 v[76:79], v[128:131], v[186:189], v[76:79]
	v_mfma_f32_16x16x32_bf16 v[72:75], v[136:139], v[186:189], v[72:75]
	v_mfma_f32_16x16x32_bf16 v[124:127], v[132:135], v[148:151], v[124:127]
	v_mfma_f32_16x16x32_bf16 v[120:123], v[140:143], v[148:151], v[120:123]
	v_mfma_f32_16x16x32_bf16 v[108:111], v[132:135], v[174:177], v[108:111]
	v_mfma_f32_16x16x32_bf16 v[104:107], v[140:143], v[174:177], v[104:107]
	v_mfma_f32_16x16x32_bf16 v[92:95], v[132:135], v[182:185], v[92:95]
	v_mfma_f32_16x16x32_bf16 v[88:91], v[140:143], v[182:185], v[88:91]
	v_mfma_f32_16x16x32_bf16 v[76:79], v[132:135], v[190:193], v[76:79]
	v_mfma_f32_16x16x32_bf16 v[72:75], v[140:143], v[190:193], v[72:75]
	s_setprio 0
	s_barrier
	s_add_i32 s40, 0, 0x1c000
	s_add_u32 s18, s14, 0x4000
	s_addc_u32 s19, s15, 0
	s_add_i32 s39, s39, s23
	v_add_u32_e32 v152, s40, v170
	v_lshl_add_u64 v[210:211], s[18:19], 0, v[156:157]
	s_mov_b32 m0, s39
	ds_read_b128 v[194:197], v152
	ds_read_b128 v[198:201], v152 offset:1024
	ds_read_b128 v[202:205], v152 offset:2048
	ds_read_b128 v[206:209], v152 offset:3072
	global_load_lds_dwordx4 v[210:211], off
	s_add_i32 m0, s39, 0x2000
	v_lshl_add_u64 v[210:211], s[18:19], 0, v[158:159]
	global_load_lds_dwordx4 v[210:211], off
	s_barrier
	s_waitcnt lgkmcnt(0)
	s_setprio 1
	v_mfma_f32_16x16x32_bf16 v[116:119], v[194:197], v[144:147], v[116:119]
	v_mfma_f32_16x16x32_bf16 v[112:115], v[202:205], v[144:147], v[112:115]
	s_mov_b32 m0, s29
	v_lshl_add_u64 v[210:211], s[16:17], 0, v[156:157]
	v_mfma_f32_16x16x32_bf16 v[100:103], v[194:197], v[166:169], v[100:103]
	v_mfma_f32_16x16x32_bf16 v[96:99], v[202:205], v[166:169], v[96:99]
	v_mfma_f32_16x16x32_bf16 v[84:87], v[194:197], v[178:181], v[84:87]
	v_mfma_f32_16x16x32_bf16 v[80:83], v[202:205], v[178:181], v[80:83]
	v_mfma_f32_16x16x32_bf16 v[68:71], v[194:197], v[186:189], v[68:71]
	v_mfma_f32_16x16x32_bf16 v[64:67], v[202:205], v[186:189], v[64:67]
	v_mfma_f32_16x16x32_bf16 v[116:119], v[198:201], v[148:151], v[116:119]
	v_mfma_f32_16x16x32_bf16 v[112:115], v[206:209], v[148:151], v[112:115]
	v_mfma_f32_16x16x32_bf16 v[100:103], v[198:201], v[174:177], v[100:103]
	v_mfma_f32_16x16x32_bf16 v[96:99], v[206:209], v[174:177], v[96:99]
	v_mfma_f32_16x16x32_bf16 v[84:87], v[198:201], v[182:185], v[84:87]
	v_mfma_f32_16x16x32_bf16 v[80:83], v[206:209], v[182:185], v[80:83]
	v_mfma_f32_16x16x32_bf16 v[68:71], v[198:201], v[190:193], v[68:71]
	v_mfma_f32_16x16x32_bf16 v[64:67], v[206:209], v[190:193], v[64:67]
	s_setprio 0
	s_barrier
	ds_read_b128 v[144:147], v172 offset:49152
	ds_read_b128 v[148:151], v172 offset:50176
	ds_read_b128 v[166:169], v172 offset:51200
	ds_read_b128 v[174:177], v172 offset:52224
	ds_read_b128 v[178:181], v172 offset:53248
	ds_read_b128 v[182:185], v172 offset:54272
	ds_read_b128 v[186:189], v172 offset:55296
	ds_read_b128 v[190:193], v172 offset:56320
	global_load_lds_dwordx4 v[210:211], off
	s_mov_b32 m0, s30
	v_lshl_add_u64 v[210:211], s[16:17], 0, v[158:159]
	global_load_lds_dwordx4 v[210:211], off
	s_barrier
; #define PG8_STAGE(bufoff, gbase, voff) do { _Pragma("unroll") for (int _i = 0; _i < 2; ++_i) \
;         __builtin_amdgcn_global_load_lds((const unsigned*)((const char*)(gbase) + (voff)[_i]), (LAS unsigned*)(lds + (bufoff) + ldsw + _i * 8192), 16, 0, 0); } while (0)
; #define PG8_MMA(ai, bj, At, Bt) do { __builtin_amdgcn_s_setprio(1); _Pragma("unroll") for (int m = 0; m < 4; ++m) _Pragma("unroll") for (int n = 0; n < 2; ++n) _Pragma("unroll") for (int k = 0; k < 2; ++k) \
;         acc[ai][bj][m][n] = __builtin_amdgcn_mfma_f32_16x16x32_bf16(Bt[n][k], At[m][k], acc[ai][bj][m][n], 0, 0, 0); __builtin_amdgcn_s_setprio(0); } while (0)
; #define PG8_WAIT_V(n) asm volatile("s_waitcnt vmcnt(" #n ")" ::: "memory")
; #define PG8_WAIT_L(n) asm volatile("s_waitcnt lgkmcnt(" #n ")" ::: "memory")
; #define PG8_BAR __builtin_amdgcn_s_barrier()
; #define PG8_SCHED __builtin_amdgcn_sched_barrier(0)
; template <class Epi>
; __device__ __forceinline__ void gemm_phase(LAS unsigned char* lds, const Gemm g, const StaticOrder& S, const Epi& E) {
;     ...
;             PG8_BAR; PG8_WAIT_L(0); PG8_MMA(1, 0, At, B0); PG8_BAR; PG8_SCHED;
;             PG8_STAGE(PG8_SB(1, 1), b3 + hstepB, voffB);
;             PG8_WAIT_V(6); PG8_BAR; PG8_MMA(1, 1, At, B1); PG8_BAR;
;     __device__ __forceinline__ void operator()(const f32x4 (&acc)[2][2][4][2], const Unit& u, int wr, int wc, int fr, int fq) const {
;         const int row0 = u.pm * BM + wr * 64 + fr, j0 = wc * 16 + 4 * fq, colb = u.pn * BM + j0;
;         if (u.pn < 8) {
	s_waitcnt lgkmcnt(0)
	s_setprio 1
	v_mfma_f32_16x16x32_bf16 v[60:63], v[128:131], v[144:147], v[60:63]
	v_mfma_f32_16x16x32_bf16 v[56:59], v[136:139], v[144:147], v[56:59]
	v_mfma_f32_16x16x32_bf16 v[44:47], v[128:131], v[166:169], v[44:47]
	v_mfma_f32_16x16x32_bf16 v[40:43], v[136:139], v[166:169], v[40:43]
	v_mfma_f32_16x16x32_bf16 v[28:31], v[128:131], v[178:181], v[28:31]
	v_mfma_f32_16x16x32_bf16 v[24:27], v[136:139], v[178:181], v[24:27]
	v_mfma_f32_16x16x32_bf16 v[12:15], v[128:131], v[186:189], v[12:15]
	v_mfma_f32_16x16x32_bf16 v[8:11], v[136:139], v[186:189], v[8:11]
	v_mfma_f32_16x16x32_bf16 v[60:63], v[132:135], v[148:151], v[60:63]
	v_mfma_f32_16x16x32_bf16 v[56:59], v[140:143], v[148:151], v[56:59]
	v_mfma_f32_16x16x32_bf16 v[44:47], v[132:135], v[174:177], v[44:47]
	v_mfma_f32_16x16x32_bf16 v[40:43], v[140:143], v[174:177], v[40:43]
	v_mfma_f32_16x16x32_bf16 v[28:31], v[132:135], v[182:185], v[28:31]
	v_mfma_f32_16x16x32_bf16 v[24:27], v[140:143], v[182:185], v[24:27]
	v_mfma_f32_16x16x32_bf16 v[12:15], v[132:135], v[190:193], v[12:15]
	v_mfma_f32_16x16x32_bf16 v[8:11], v[140:143], v[190:193], v[8:11]
	s_setprio 0
	s_barrier
	s_add_u32 s14, s14, 0x84000
	s_addc_u32 s15, s15, 0
	s_add_i32 s16, s40, s23
	s_mov_b32 m0, s16
	v_lshl_add_u64 v[128:129], s[14:15], 0, v[156:157]
	global_load_lds_dwordx4 v[128:129], off
	s_add_i32 m0, s16, 0x2000
	v_lshl_add_u64 v[128:129], s[14:15], 0, v[158:159]
	global_load_lds_dwordx4 v[128:129], off
	s_waitcnt vmcnt(6)
	s_barrier
	s_setprio 1
	v_mfma_f32_16x16x32_bf16 v[52:55], v[194:197], v[144:147], v[52:55]
	v_mfma_f32_16x16x32_bf16 v[48:51], v[202:205], v[144:147], v[48:51]
	s_add_i32 s38, s38, 2
	s_add_u32 s12, s12, 0x8000
	s_addc_u32 s13, s13, 0
	s_add_u32 s36, s36, 0x8000
	s_addc_u32 s37, s37, 0
	v_mfma_f32_16x16x32_bf16 v[36:39], v[194:197], v[166:169], v[36:39]
	v_mfma_f32_16x16x32_bf16 v[32:35], v[202:205], v[166:169], v[32:35]
	v_mfma_f32_16x16x32_bf16 v[20:23], v[194:197], v[178:181], v[20:23]
	v_mfma_f32_16x16x32_bf16 v[16:19], v[202:205], v[178:181], v[16:19]
	v_mfma_f32_16x16x32_bf16 v[4:7], v[194:197], v[186:189], v[4:7]
	v_mfma_f32_16x16x32_bf16 v[0:3], v[202:205], v[186:189], v[0:3]
	v_mfma_f32_16x16x32_bf16 v[52:55], v[198:201], v[148:151], v[52:55]
	v_mfma_f32_16x16x32_bf16 v[48:51], v[206:209], v[148:151], v[48:51]
	v_mfma_f32_16x16x32_bf16 v[36:39], v[198:201], v[174:177], v[36:39]
	v_mfma_f32_16x16x32_bf16 v[32:35], v[206:209], v[174:177], v[32:35]
	v_mfma_f32_16x16x32_bf16 v[20:23], v[198:201], v[182:185], v[20:23]
	v_mfma_f32_16x16x32_bf16 v[16:19], v[206:209], v[182:185], v[16:19]
	v_mfma_f32_16x16x32_bf16 v[4:7], v[198:201], v[190:193], v[4:7]
	v_mfma_f32_16x16x32_bf16 v[0:3], v[206:209], v[190:193], v[0:3]
	s_setprio 0
	s_cmp_gt_u32 s38, 29
	s_barrier
	s_cbranch_scc0 .LBB0_247
	v_lshl_add_u32 v177, s10, 8, v165
	v_lshl_or_b32 v152, s34, 8, v171
	s_mov_b64 s[10:11], -1
	s_cmp_lt_i32 s34, 8
	v_or_b32_e32 v180, 16, v177
	v_or_b32_e32 v179, 32, v177
	v_or_b32_e32 v178, 48, v177
	v_add_u32_e32 v176, 0x80, v177
	v_add_u32_e32 v175, 0x90, v177
	v_add_u32_e32 v174, 0xa0, v177
	v_add_u32_e32 v173, 0xb0, v177
	s_cbranch_scc1 .LBB0_250
; __device__ __forceinline__ unsigned cvt_pk_bf16(float lo, float hi) { unsigned r; asm volatile("v_cvt_pk_bf16_f32 %0, %1, %2" : "=v"(r) : "v"(lo), "v"(hi)); return r; }
;     __device__ __forceinline__ void operator()(const f32x4 (&acc)[2][2][4][2], const Unit& u, int wr, int wc, int fr, int fq) const {
;     ...
; #pragma unroll
;             for (int ai = 0; ai < 2; ++ai)
; #pragma unroll
;                 for (int m = 0; m < 4; ++m) {
;                     const int row = row0 + ai * HALF + m * 16;
;                     bf16_t* rowp = O + (size_t)row * DIN + colb;
; #pragma unroll
;                     for (int bj = 0; bj < 2; ++bj) {
;                         const f32x4 o1 = acc[ai][bj][m][0], o2 = acc[ai][bj][m][1];
;                         u32x2 w1, w2; w1.x = cvt_pk_bf16(o1[0], o1[1]); w1.y = cvt_pk_bf16(o1[2], o1[3]); w2.x = cvt_pk_bf16(o2[0], o2[1]); w2.y = cvt_pk_bf16(o2[2], o2[3]);
;                         *(u32x2*)(rowp + bj * HALF) = w1; *(u32x2*)(rowp + bj * HALF + 64) = w2;
;                     }
;                 }
	v_readlane_b32 s10, v252, 57
	v_readlane_b32 s11, v252, 58
	s_movk_i32 s3, 0x3000
	v_lshlrev_b64 v[130:131], 1, v[152:153]
	v_mov_b64_e32 v[128:129], s[10:11]
	v_mad_i64_i32 v[132:133], s[10:11], v177, s3, v[128:129]
	v_lshl_add_u64 v[132:133], v[132:133], 0, v[130:131]
	v_cvt_pk_bf16_f32 v134, v124, v125
	v_cvt_pk_bf16_f32 v135, v126, v127
	v_cvt_pk_bf16_f32 v136, v120, v121
	v_cvt_pk_bf16_f32 v137, v122, v123
	global_store_dwordx2 v[132:133], v[134:135], off
	global_store_dwordx2 v[132:133], v[136:137], off offset:128
	v_cvt_pk_bf16_f32 v134, v116, v117
	v_cvt_pk_bf16_f32 v135, v118, v119
	v_cvt_pk_bf16_f32 v136, v112, v113
	v_cvt_pk_bf16_f32 v137, v114, v115
	global_store_dwordx2 v[132:133], v[134:135], off offset:256
	global_store_dwordx2 v[132:133], v[136:137], off offset:384
	v_mad_i64_i32 v[132:133], s[10:11], v180, s3, v[128:129]
	v_lshl_add_u64 v[132:133], v[132:133], 0, v[130:131]
	v_cvt_pk_bf16_f32 v134, v108, v109
	v_cvt_pk_bf16_f32 v135, v110, v111
	v_cvt_pk_bf16_f32 v136, v104, v105
	v_cvt_pk_bf16_f32 v137, v106, v107
	global_store_dwordx2 v[132:133], v[134:135], off
	global_store_dwordx2 v[132:133], v[136:137], off offset:128
	v_cvt_pk_bf16_f32 v134, v100, v101
	v_cvt_pk_bf16_f32 v135, v102, v103
	v_cvt_pk_bf16_f32 v136, v96, v97
	v_cvt_pk_bf16_f32 v137, v98, v99
	global_store_dwordx2 v[132:133], v[134:135], off offset:256
	global_store_dwordx2 v[132:133], v[136:137], off offset:384
	v_mad_i64_i32 v[132:133], s[10:11], v179, s3, v[128:129]
	v_lshl_add_u64 v[132:133], v[132:133], 0, v[130:131]
	v_cvt_pk_bf16_f32 v134, v92, v93
	v_cvt_pk_bf16_f32 v135, v94, v95
	v_cvt_pk_bf16_f32 v136, v88, v89
	v_cvt_pk_bf16_f32 v137, v90, v91
	global_store_dwordx2 v[132:133], v[134:135], off
	global_store_dwordx2 v[132:133], v[136:137], off offset:128
	v_cvt_pk_bf16_f32 v134, v84, v85
	v_cvt_pk_bf16_f32 v135, v86, v87
	v_cvt_pk_bf16_f32 v136, v80, v81
	v_cvt_pk_bf16_f32 v137, v82, v83
	global_store_dwordx2 v[132:133], v[134:135], off offset:256
	global_store_dwordx2 v[132:133], v[136:137], off offset:384
	v_mad_i64_i32 v[132:133], s[10:11], v178, s3, v[128:129]
	v_lshl_add_u64 v[132:133], v[132:133], 0, v[130:131]
	v_cvt_pk_bf16_f32 v134, v76, v77
	v_cvt_pk_bf16_f32 v135, v78, v79
	v_cvt_pk_bf16_f32 v136, v72, v73
	v_cvt_pk_bf16_f32 v137, v74, v75
	global_store_dwordx2 v[132:133], v[134:135], off
	global_store_dwordx2 v[132:133], v[136:137], off offset:128
	v_cvt_pk_bf16_f32 v134, v68, v69
	v_cvt_pk_bf16_f32 v135, v70, v71
	v_cvt_pk_bf16_f32 v136, v64, v65
	v_cvt_pk_bf16_f32 v137, v66, v67
	global_store_dwordx2 v[132:133], v[134:135], off offset:256
	global_store_dwordx2 v[132:133], v[136:137], off offset:384
	v_mad_i64_i32 v[132:133], s[10:11], v176, s3, v[128:129]
	v_lshl_add_u64 v[132:133], v[132:133], 0, v[130:131]
	v_cvt_pk_bf16_f32 v134, v60, v61
	v_cvt_pk_bf16_f32 v135, v62, v63
	v_cvt_pk_bf16_f32 v136, v56, v57
	v_cvt_pk_bf16_f32 v137, v58, v59
	global_store_dwordx2 v[132:133], v[134:135], off
	global_store_dwordx2 v[132:133], v[136:137], off offset:128
	v_cvt_pk_bf16_f32 v134, v52, v53
	v_cvt_pk_bf16_f32 v135, v54, v55
	v_cvt_pk_bf16_f32 v136, v48, v49
	v_cvt_pk_bf16_f32 v137, v50, v51
	global_store_dwordx2 v[132:133], v[134:135], off offset:256
	global_store_dwordx2 v[132:133], v[136:137], off offset:384
	v_mad_i64_i32 v[132:133], s[10:11], v175, s3, v[128:129]
	v_lshl_add_u64 v[132:133], v[132:133], 0, v[130:131]
	v_cvt_pk_bf16_f32 v134, v44, v45
	v_cvt_pk_bf16_f32 v135, v46, v47
	v_cvt_pk_bf16_f32 v136, v40, v41
	v_cvt_pk_bf16_f32 v137, v42, v43
	global_store_dwordx2 v[132:133], v[134:135], off
	global_store_dwordx2 v[132:133], v[136:137], off offset:128
	v_cvt_pk_bf16_f32 v134, v36, v37
	v_cvt_pk_bf16_f32 v135, v38, v39
	v_cvt_pk_bf16_f32 v136, v32, v33
	v_cvt_pk_bf16_f32 v137, v34, v35
	global_store_dwordx2 v[132:133], v[134:135], off offset:256
	global_store_dwordx2 v[132:133], v[136:137], off offset:384
	v_mad_i64_i32 v[132:133], s[10:11], v174, s3, v[128:129]
	v_lshl_add_u64 v[132:133], v[132:133], 0, v[130:131]
	v_cvt_pk_bf16_f32 v134, v28, v29
	v_cvt_pk_bf16_f32 v135, v30, v31
	v_cvt_pk_bf16_f32 v136, v24, v25
	v_cvt_pk_bf16_f32 v137, v26, v27
	global_store_dwordx2 v[132:133], v[134:135], off
	global_store_dwordx2 v[132:133], v[136:137], off offset:128
	v_cvt_pk_bf16_f32 v134, v20, v21
	v_cvt_pk_bf16_f32 v135, v22, v23
	v_mad_i64_i32 v[128:129], s[10:11], v173, s3, v[128:129]
	v_cvt_pk_bf16_f32 v136, v16, v17
	v_cvt_pk_bf16_f32 v137, v18, v19
	global_store_dwordx2 v[132:133], v[134:135], off offset:256
	global_store_dwordx2 v[132:133], v[136:137], off offset:384
	v_lshl_add_u64 v[128:129], v[128:129], 0, v[130:131]
	v_cvt_pk_bf16_f32 v130, v12, v13
	v_cvt_pk_bf16_f32 v131, v14, v15
	v_cvt_pk_bf16_f32 v132, v8, v9
	v_cvt_pk_bf16_f32 v133, v10, v11
	s_mov_b64 s[10:11], 0
	global_store_dwordx2 v[128:129], v[130:131], off
	global_store_dwordx2 v[128:129], v[132:133], off offset:128
	v_cvt_pk_bf16_f32 v130, v4, v5
	v_cvt_pk_bf16_f32 v131, v6, v7
	v_cvt_pk_bf16_f32 v132, v0, v1
	v_cvt_pk_bf16_f32 v133, v2, v3
